# pipelined diff-attn tile loop + rescheduled natten tile loop + hoisted subln-gain loads in attn epilogue
# speedup vs baseline: 1.0292x; 1.0292x over previous
; #define LAS __attribute__((address_space(3)))
; __device__ __forceinline__ unsigned cvtpk(float lo, float hi) { f32x2_t v = {lo, hi}; bf16x2_t b = __builtin_convertvector(v, bf16x2_t); return __builtin_bit_cast(unsigned, b); }
; #define A_BAR() asm volatile("s_waitcnt lgkmcnt(0)\n\ts_barrier" ::: "memory")
; __device__ __forceinline__ void attn_unit_A(const AttnP& P, int u, LAS char* lds) {
;     ...
;     for (int t = 0; t < nt; ++t) {
;         const bool more = (t + 1 < nt);
;         if (more) { A_WRITE(bnext); if (t + 2 < nt) A_ISSUE(t + 2); }
;         int clsn = clsk;
;         if (more) { clsn = A_CLS(t + 1);
;             if (clsn != clsk) { const float dc = A_CVAL(clsn) - A_CVAL(clsk); clsk = clsn;
; #pragma unroll
;                 for (int r = 0; r < 16; ++r) negc[r] += dc; } }
;     ...
;         const LAS char* vbase = lds + bcur + 2 * AKS + vrow * AVP + vcolb;
;     ...
;         bf16x8 vfa[4], vfb[4];
;         A_VLOAD(vfa, 0);
;         __builtin_amdgcn_sched_barrier(0);
;         float sacc = 0.f;
; #pragma unroll
;         for (int r = 0; r < 16; ++r) { sa0[r] = __builtin_amdgcn_exp2f(sa0[r]); sa1[r] = __builtin_amdgcn_exp2f(sa1[r]); sacc += sa0[r] + sa1[r]; }
;         lrun += sacc;
;         bf16x8 pf[4];
;         { u32x4 a;
;           a.x = cvtpk(sa0[0], sa0[1]); a.y = cvtpk(sa0[2], sa0[3]); a.z = cvtpk(sa0[4], sa0[5]); a.w = cvtpk(sa0[6], sa0[7]); pf[0] = __builtin_bit_cast(bf16x8, a);
;           a.x = cvtpk(sa0[8], sa0[9]); a.y = cvtpk(sa0[10], sa0[11]); a.z = cvtpk(sa0[12], sa0[13]); a.w = cvtpk(sa0[14], sa0[15]); pf[1] = __builtin_bit_cast(bf16x8, a);
;           a.x = cvtpk(sa1[0], sa1[1]); a.y = cvtpk(sa1[2], sa1[3]); a.z = cvtpk(sa1[4], sa1[5]); a.w = cvtpk(sa1[6], sa1[7]); pf[2] = __builtin_bit_cast(bf16x8, a);
;           a.x = cvtpk(sa1[8], sa1[9]); a.y = cvtpk(sa1[10], sa1[11]); a.z = cvtpk(sa1[12], sa1[13]); a.w = cvtpk(sa1[14], sa1[15]); pf[3] = __builtin_bit_cast(bf16x8, a); }
;         __builtin_amdgcn_sched_barrier(0);
;         A_VLOAD(vfb, 1);
;         __builtin_amdgcn_sched_barrier(0);
;         A_VMMA(vfa, 0);
;         A_VLOAD(vfa, 2);
;         __builtin_amdgcn_sched_barrier(0);
;         A_VMMA(vfb, 1);
;         A_VLOAD(vfb, 3);
;         __builtin_amdgcn_sched_barrier(0);
;         A_VMMA(vfa, 2);
;         __builtin_amdgcn_sched_barrier(0);
;         A_VMMA(vfb, 3);
;     ...
;         __builtin_amdgcn_sched_barrier(0); A_BAR(); A_QKBLK();
.LBB0_656:
	v_add3_u32 v238, s29, v178, v160
	v_add3_u32 v239, s29, v180, v160
	s_waitcnt vmcnt(3)
	ds_write_b128 v238, v[156:159]
	s_waitcnt vmcnt(2)
	ds_write_b128 v238, v[152:155] offset:9216
	s_waitcnt vmcnt(1)
	ds_write_b128 v239, v[148:151] offset:18432
	s_waitcnt vmcnt(0)
	ds_write_b128 v239, v[144:147] offset:30720
	v_add_u32_e32 v238, s35, v181
	v_min_i32_e32 v238, 0x100f, v238
	v_mad_i64_i32 v[192:193], s[0:1], v238, s51, v[162:163]
	global_load_dwordx4 v[156:159], v[192:193], off offset:1024
	global_load_dwordx4 v[152:155], v[192:193], off offset:1152
	global_load_dwordx4 v[148:151], v[192:193], off offset:2048
	global_load_dwordx4 v[144:147], v[192:193], off offset:2176
	v_mov_b32_e32 v206, v96
	v_mov_b32_e32 v0, v112
	v_mov_b32_e32 v207, v97
	v_mov_b32_e32 v1, v113
	v_mov_b32_e32 v208, v98
	v_mov_b32_e32 v2, v114
	v_mov_b32_e32 v209, v99
	v_mov_b32_e32 v3, v115
	v_mov_b32_e32 v210, v100
	v_mov_b32_e32 v4, v116
	v_mov_b32_e32 v211, v101
	v_mov_b32_e32 v5, v117
	v_mov_b32_e32 v212, v102
	v_mov_b32_e32 v6, v118
	v_mov_b32_e32 v213, v103
	v_mov_b32_e32 v7, v119
	v_mov_b32_e32 v214, v104
	v_mov_b32_e32 v8, v120
	v_mov_b32_e32 v215, v105
	v_mov_b32_e32 v9, v121
	v_mov_b32_e32 v216, v106
	v_mov_b32_e32 v10, v122
	v_mov_b32_e32 v217, v107
	v_mov_b32_e32 v11, v123
	v_mov_b32_e32 v218, v108
	v_mov_b32_e32 v12, v124
	v_mov_b32_e32 v219, v109
	v_mov_b32_e32 v13, v125
	v_mov_b32_e32 v220, v110
	v_mov_b32_e32 v14, v126
	v_mov_b32_e32 v221, v111
	v_mov_b32_e32 v15, v127
	v_mov_b32_e32 v202, 0
	s_mov_b32 s38, 0x15000
	s_waitcnt lgkmcnt(0)
	s_barrier
.Latt1_loop:
	s_add_i32 s0, s28, s35
	s_add_i32 s31, s35, 64
	s_add_i32 s0, s0, 33
	s_cmpk_gt_i32 s0, 0x7f
	s_cselect_b32 s0, 2, 1
	s_cmp_gt_i32 s31, s16
	s_cselect_b32 s30, s0, 0
	s_cmp_eq_u32 s30, s39
	s_cbranch_scc1 .Latt1_e_same
	s_cmp_eq_u32 s30, 2
	s_cselect_b32 s0, 1, 0
	s_lshl_b32 s0, s0, 10
	s_add_i32 s0, s0, 0x1f800
	s_cmp_eq_u32 s39, 2
	s_cselect_b32 s1, 1, 0
	s_lshl_b32 s1, s1, 10
	s_add_i32 s1, s1, 0x1f800
	v_mov_b32_e32 v238, s0
	v_mov_b32_e32 v239, s1
	ds_read_b32 v238, v238
	ds_read_b32 v239, v239
	s_cmp_eq_u32 s30, 1
	s_cselect_b32 s0, 0, 0x3f800000
	s_cmp_eq_u32 s39, 1
	s_cselect_b32 s1, 0, 0x3f800000
	s_waitcnt lgkmcnt(0)
	v_mul_f32_e32 v238, s0, v238
	v_mul_f32_e32 v239, s1, v239
	v_sub_f32_e32 v238, v238, v239
	v_add_f32_e32 v80, v80, v238
	v_add_f32_e32 v81, v81, v238
	v_add_f32_e32 v82, v82, v238
	v_add_f32_e32 v83, v83, v238
	v_add_f32_e32 v84, v84, v238
	v_add_f32_e32 v85, v85, v238
	v_add_f32_e32 v86, v86, v238
	v_add_f32_e32 v87, v87, v238
	v_add_f32_e32 v88, v88, v238
	v_add_f32_e32 v89, v89, v238
	v_add_f32_e32 v90, v90, v238
	v_add_f32_e32 v91, v91, v238
	v_add_f32_e32 v92, v92, v238
	v_add_f32_e32 v93, v93, v238
	v_add_f32_e32 v94, v94, v238
	v_add_f32_e32 v95, v95, v238
.Latt1_e_same:
	v_add_u32_e32 v203, s29, v174
	v_add_u32_e32 v235, s26, v182
	s_cmp_eq_u32 s30, 1
	s_cbranch_scc1 .Latt1_e_near
	ds_read_b128 v[184:187], v203
	ds_read_b128 v[188:191], v203 offset:4608
	ds_read_b128 v[222:225], v203 offset:32
	ds_read_b128 v[226:229], v203 offset:4640
	ds_read_b128 v[230:233], v203 offset:64
	ds_read_b128 v[244:247], v203 offset:4672
	ds_read_b128 v[248:251], v203 offset:96
	v_exp_f32_e32 v206, v206
	v_exp_f32_e32 v207, v207
	v_exp_f32_e32 v208, v208
	v_exp_f32_e32 v209, v209
	v_exp_f32_e32 v210, v210
	v_exp_f32_e32 v211, v211
	v_exp_f32_e32 v212, v212
	v_exp_f32_e32 v213, v213
	s_waitcnt lgkmcnt(6)
	v_mfma_f32_32x32x16_bf16 v[96:111], v[184:187], v[140:143], v[80:95]
	ds_read_b128 v[184:187], v203 offset:4704
	v_add_f32_e32 v179, v179, v206
	v_add_f32_e32 v202, v202, v207
	v_add_f32_e32 v179, v179, v208
	v_add_f32_e32 v202, v202, v209
	v_exp_f32_e32 v214, v214
	s_waitcnt lgkmcnt(6)
	v_mfma_f32_32x32x16_bf16 v[112:127], v[188:191], v[140:143], v[80:95]
	ds_read_b64_tr_b16 v[188:189], v235 offset:18432
	ds_read_b64_tr_b16 v[190:191], v235 offset:19968
	v_add_f32_e32 v179, v179, v210
	v_add_f32_e32 v202, v202, v211
	v_add_f32_e32 v179, v179, v212
	v_add_f32_e32 v202, v202, v213
	v_exp_f32_e32 v215, v215
	s_branch .Latt1_e_join
.Latt1_e_near:
	v_add_u32_e32 v238, s35, v183
	s_add_i32 s0, 0, 0x1f800
	v_add_u32_e32 v96, 0x40, v238
	v_med3_i32 v96, v96, s87, v240
	v_lshl_add_u32 v96, v96, 2, s0
	v_add_u32_e32 v97, 0x41, v238
	v_med3_i32 v97, v97, s87, v240
	v_lshl_add_u32 v97, v97, 2, s0
	v_add_u32_e32 v98, 0x42, v238
	v_med3_i32 v98, v98, s87, v240
	v_lshl_add_u32 v98, v98, 2, s0
	v_add_u32_e32 v99, 0x43, v238
	v_med3_i32 v99, v99, s87, v240
	v_lshl_add_u32 v99, v99, 2, s0
	v_add_u32_e32 v100, 0x48, v238
	v_med3_i32 v100, v100, s87, v240
	v_lshl_add_u32 v100, v100, 2, s0
	v_add_u32_e32 v101, 0x49, v238
	v_med3_i32 v101, v101, s87, v240
	v_lshl_add_u32 v101, v101, 2, s0
	v_add_u32_e32 v102, 0x4a, v238
	v_med3_i32 v102, v102, s87, v240
	v_lshl_add_u32 v102, v102, 2, s0
	v_add_u32_e32 v103, 0x4b, v238
	v_med3_i32 v103, v103, s87, v240
	v_lshl_add_u32 v103, v103, 2, s0
	v_add_u32_e32 v104, 0x50, v238
	v_med3_i32 v104, v104, s87, v240
	v_lshl_add_u32 v104, v104, 2, s0
	v_add_u32_e32 v105, 0x51, v238
	v_med3_i32 v105, v105, s87, v240
	v_lshl_add_u32 v105, v105, 2, s0
	v_add_u32_e32 v106, 0x52, v238
	v_med3_i32 v106, v106, s87, v240
	v_lshl_add_u32 v106, v106, 2, s0
	v_add_u32_e32 v107, 0x53, v238
	v_med3_i32 v107, v107, s87, v240
	v_lshl_add_u32 v107, v107, 2, s0
	v_add_u32_e32 v108, 0x58, v238
	v_med3_i32 v108, v108, s87, v240
	v_lshl_add_u32 v108, v108, 2, s0
	v_add_u32_e32 v109, 0x59, v238
	v_med3_i32 v109, v109, s87, v240
	v_lshl_add_u32 v109, v109, 2, s0
	v_add_u32_e32 v110, 0x5a, v238
	v_med3_i32 v110, v110, s87, v240
	v_lshl_add_u32 v110, v110, 2, s0
; #define LAS __attribute__((address_space(3)))
; #define A_VLOAD(dst, d) do { const LAS char* vb_ = vbase + ((d) >> 1) * AVS + ((d) & 1) * 64; \
;         _Pragma("unroll") for (int ks = 0; ks < 4; ++ks) { const s16x4 vl_ = vtr(vb_ + (16 * ks) * AVP), vh_ = vtr(vb_ + (16 * ks + 8) * AVP); \
;             dst[ks] = (bf16x8){vl_[0], vl_[1], vl_[2], vl_[3], vh_[0], vh_[1], vh_[2], vh_[3]}; } } while (0)
; __device__ __forceinline__ void attn_unit_A(const AttnP& P, int u, LAS char* lds) {
;     ...
;         const LAS char* vbase = lds + bcur + 2 * AKS + vrow * AVP + vcolb;
;     ...
;         bf16x8 vfa[4], vfb[4];
;         A_VLOAD(vfa, 0);
;         __builtin_amdgcn_sched_barrier(0);
;         float sacc = 0.f;
; #pragma unroll
;         for (int r = 0; r < 16; ++r) { sa0[r] = __builtin_amdgcn_exp2f(sa0[r]); sa1[r] = __builtin_amdgcn_exp2f(sa1[r]); sacc += sa0[r] + sa1[r]; }
	v_add_u32_e32 v111, 0x5b, v238
	v_med3_i32 v111, v111, s87, v240
	v_lshl_add_u32 v111, v111, 2, s0
	ds_read_b32 v96, v96 offset:512
	ds_read_b32 v97, v97 offset:512
	ds_read_b32 v98, v98 offset:512
	ds_read_b32 v99, v99 offset:512
	ds_read_b32 v100, v100 offset:512
	ds_read_b32 v101, v101 offset:512
	ds_read_b32 v102, v102 offset:512
	ds_read_b32 v103, v103 offset:512
	ds_read_b32 v104, v104 offset:512
	ds_read_b32 v105, v105 offset:512
	ds_read_b32 v106, v106 offset:512
	ds_read_b32 v107, v107 offset:512
	ds_read_b32 v108, v108 offset:512
	ds_read_b32 v109, v109 offset:512
	ds_read_b32 v110, v110 offset:512
	ds_read_b32 v111, v111 offset:512
	v_add_u32_e32 v112, 0x60, v238
	v_med3_i32 v112, v112, s87, v240
	v_lshl_add_u32 v112, v112, 2, s0
	v_add_u32_e32 v113, 0x61, v238
	v_med3_i32 v113, v113, s87, v240
	v_lshl_add_u32 v113, v113, 2, s0
	v_add_u32_e32 v114, 0x62, v238
	v_med3_i32 v114, v114, s87, v240
	v_lshl_add_u32 v114, v114, 2, s0
	v_add_u32_e32 v115, 0x63, v238
	v_med3_i32 v115, v115, s87, v240
	v_lshl_add_u32 v115, v115, 2, s0
	v_add_u32_e32 v116, 0x68, v238
	v_med3_i32 v116, v116, s87, v240
	v_lshl_add_u32 v116, v116, 2, s0
	v_add_u32_e32 v117, 0x69, v238
	v_med3_i32 v117, v117, s87, v240
	v_lshl_add_u32 v117, v117, 2, s0
	v_add_u32_e32 v118, 0x6a, v238
	v_med3_i32 v118, v118, s87, v240
	v_lshl_add_u32 v118, v118, 2, s0
	v_add_u32_e32 v119, 0x6b, v238
	v_med3_i32 v119, v119, s87, v240
	v_lshl_add_u32 v119, v119, 2, s0
	v_add_u32_e32 v120, 0x70, v238
	v_med3_i32 v120, v120, s87, v240
	v_lshl_add_u32 v120, v120, 2, s0
	v_add_u32_e32 v121, 0x71, v238
	v_med3_i32 v121, v121, s87, v240
	v_lshl_add_u32 v121, v121, 2, s0
	v_add_u32_e32 v122, 0x72, v238
	v_med3_i32 v122, v122, s87, v240
	v_lshl_add_u32 v122, v122, 2, s0
	v_add_u32_e32 v123, 0x73, v238
	v_med3_i32 v123, v123, s87, v240
	v_lshl_add_u32 v123, v123, 2, s0
	v_add_u32_e32 v124, 0x78, v238
	v_med3_i32 v124, v124, s87, v240
	v_lshl_add_u32 v124, v124, 2, s0
	v_add_u32_e32 v125, 0x79, v238
	v_med3_i32 v125, v125, s87, v240
	v_lshl_add_u32 v125, v125, 2, s0
	v_add_u32_e32 v126, 0x7a, v238
	v_med3_i32 v126, v126, s87, v240
	v_lshl_add_u32 v126, v126, 2, s0
	v_add_u32_e32 v127, 0x7b, v238
	v_med3_i32 v127, v127, s87, v240
	v_lshl_add_u32 v127, v127, 2, s0
	ds_read_b32 v112, v112 offset:512
	ds_read_b32 v113, v113 offset:512
	ds_read_b32 v114, v114 offset:512
	ds_read_b32 v115, v115 offset:512
	ds_read_b32 v116, v116 offset:512
	ds_read_b32 v117, v117 offset:512
	ds_read_b32 v118, v118 offset:512
	ds_read_b32 v119, v119 offset:512
	ds_read_b32 v120, v120 offset:512
	ds_read_b32 v121, v121 offset:512
	ds_read_b32 v122, v122 offset:512
	ds_read_b32 v123, v123 offset:512
	ds_read_b32 v124, v124 offset:512
	ds_read_b32 v125, v125 offset:512
	ds_read_b32 v126, v126 offset:512
	ds_read_b32 v127, v127 offset:512
	s_waitcnt lgkmcnt(0)
	v_add_f32_e32 v96, v96, v80
	v_add_f32_e32 v97, v97, v80
	v_add_f32_e32 v98, v98, v80
	v_add_f32_e32 v99, v99, v80
	v_add_f32_e32 v100, v100, v80
	v_add_f32_e32 v101, v101, v80
	v_add_f32_e32 v102, v102, v80
	v_add_f32_e32 v103, v103, v80
	v_add_f32_e32 v104, v104, v80
	v_add_f32_e32 v105, v105, v80
	v_add_f32_e32 v106, v106, v80
	v_add_f32_e32 v107, v107, v80
	v_add_f32_e32 v108, v108, v80
	v_add_f32_e32 v109, v109, v80
	v_add_f32_e32 v110, v110, v80
	v_add_f32_e32 v111, v111, v80
	v_add_f32_e32 v112, v112, v80
	v_add_f32_e32 v113, v113, v80
	v_add_f32_e32 v114, v114, v80
	v_add_f32_e32 v115, v115, v80
	v_add_f32_e32 v116, v116, v80
	v_add_f32_e32 v117, v117, v80
	v_add_f32_e32 v118, v118, v80
	v_add_f32_e32 v119, v119, v80
	v_add_f32_e32 v120, v120, v80
	v_add_f32_e32 v121, v121, v80
	v_add_f32_e32 v122, v122, v80
	v_add_f32_e32 v123, v123, v80
	v_add_f32_e32 v124, v124, v80
	v_add_f32_e32 v125, v125, v80
	v_add_f32_e32 v126, v126, v80
	v_add_f32_e32 v127, v127, v80
	ds_read_b128 v[184:187], v203
	ds_read_b128 v[188:191], v203 offset:4608
	ds_read_b128 v[222:225], v203 offset:32
	ds_read_b128 v[226:229], v203 offset:4640
	ds_read_b128 v[230:233], v203 offset:64
	ds_read_b128 v[244:247], v203 offset:4672
	ds_read_b128 v[248:251], v203 offset:96
	v_exp_f32_e32 v206, v206
	v_exp_f32_e32 v207, v207
	v_exp_f32_e32 v208, v208
	v_exp_f32_e32 v209, v209
	v_exp_f32_e32 v210, v210
	v_exp_f32_e32 v211, v211
	v_exp_f32_e32 v212, v212
	v_exp_f32_e32 v213, v213
	s_waitcnt lgkmcnt(6)
	v_mfma_f32_32x32x16_bf16 v[96:111], v[184:187], v[140:143], v[96:111]
	ds_read_b128 v[184:187], v203 offset:4704
	v_add_f32_e32 v179, v179, v206
	v_add_f32_e32 v202, v202, v207
	v_add_f32_e32 v179, v179, v208
	v_add_f32_e32 v202, v202, v209
	v_exp_f32_e32 v214, v214
	s_waitcnt lgkmcnt(6)
	v_mfma_f32_32x32x16_bf16 v[112:127], v[188:191], v[140:143], v[112:127]
	ds_read_b64_tr_b16 v[188:189], v235 offset:18432
	ds_read_b64_tr_b16 v[190:191], v235 offset:19968
	v_add_f32_e32 v179, v179, v210
	v_add_f32_e32 v202, v202, v211
	v_add_f32_e32 v179, v179, v212
	v_add_f32_e32 v202, v202, v213
	v_exp_f32_e32 v215, v215
; #define LAS __attribute__((address_space(3)))
; __device__ __forceinline__ void attn_unit_A(const AttnP& P, int u, LAS char* lds) {
;     ...
;         const LAS char* vbase = lds + bcur + 2 * AKS + vrow * AVP + vcolb;
;     ...
;         bf16x8 vfa[4], vfb[4];
;         A_VLOAD(vfa, 0);
;         __builtin_amdgcn_sched_barrier(0);
;         float sacc = 0.f;
; #pragma unroll
;         for (int r = 0; r < 16; ++r) { sa0[r] = __builtin_amdgcn_exp2f(sa0[r]); sa1[r] = __builtin_amdgcn_exp2f(sa1[r]); sacc += sa0[r] + sa1[r]; }
;         lrun += sacc;
;         bf16x8 pf[4];
;         { u32x4 a;
;           a.x = cvtpk(sa0[0], sa0[1]); a.y = cvtpk(sa0[2], sa0[3]); a.z = cvtpk(sa0[4], sa0[5]); a.w = cvtpk(sa0[6], sa0[7]); pf[0] = __builtin_bit_cast(bf16x8, a);
;           a.x = cvtpk(sa0[8], sa0[9]); a.y = cvtpk(sa0[10], sa0[11]); a.z = cvtpk(sa0[12], sa0[13]); a.w = cvtpk(sa0[14], sa0[15]); pf[1] = __builtin_bit_cast(bf16x8, a);
;           a.x = cvtpk(sa1[0], sa1[1]); a.y = cvtpk(sa1[2], sa1[3]); a.z = cvtpk(sa1[4], sa1[5]); a.w = cvtpk(sa1[6], sa1[7]); pf[2] = __builtin_bit_cast(bf16x8, a);
;           a.x = cvtpk(sa1[8], sa1[9]); a.y = cvtpk(sa1[10], sa1[11]); a.z = cvtpk(sa1[12], sa1[13]); a.w = cvtpk(sa1[14], sa1[15]); pf[3] = __builtin_bit_cast(bf16x8, a); }
;         __builtin_amdgcn_sched_barrier(0);
;         A_VLOAD(vfb, 1);
;         __builtin_amdgcn_sched_barrier(0);
;         A_VMMA(vfa, 0);
;         A_VLOAD(vfa, 2);
;         __builtin_amdgcn_sched_barrier(0);
;         A_VMMA(vfb, 1);
;         A_VLOAD(vfb, 3);
;         __builtin_amdgcn_sched_barrier(0);
;         A_VMMA(vfa, 2);
;         __builtin_amdgcn_sched_barrier(0);
;         A_VMMA(vfb, 3);
;     ...
;         __builtin_amdgcn_sched_barrier(0); A_BAR(); A_QKBLK();
;     ...
;         if (more) {
;             if (clsn == 1) A_NEAR(sa0, sa1, t + 1);
;             float mx_; A_ROWMAX(sa0, sa1, mx_);
;             if (__any(mx_ > 8.0f)) { const float dl = fmaxf(mx_, 0.f); const float f_ = __builtin_amdgcn_exp2f(-dl); lrun *= f_;
; #pragma unroll
;                 for (int r = 0; r < 16; ++r) { sa0[r] -= dl; sa1[r] -= dl; negc[r] -= dl; }
; #pragma unroll
;                 for (int d = 0; d < 4; ++d)
; #pragma unroll
;                     for (int r = 0; r < 16; ++r) o[d][r] *= f_; }
;         }
;         bcur = bnext; bnext = bnext + ABUF; if (bnext == 3 * ABUF) bnext = 0;
.Latt1_e_join:
	s_waitcnt lgkmcnt(7)
	v_mfma_f32_32x32x16_bf16 v[96:111], v[222:225], v[136:139], v[96:111]
	ds_read_b64_tr_b16 v[222:223], v235 offset:18496
	ds_read_b64_tr_b16 v[224:225], v235 offset:20032
	v_cvt_pk_bf16_f32 v206, v206, v207
	v_cvt_pk_bf16_f32 v207, v208, v209
	v_cvt_pk_bf16_f32 v208, v210, v211
	v_cvt_pk_bf16_f32 v209, v212, v213
	v_exp_f32_e32 v216, v216
	s_waitcnt lgkmcnt(8)
	v_mfma_f32_32x32x16_bf16 v[112:127], v[226:229], v[136:139], v[112:127]
	ds_read_b64_tr_b16 v[226:227], v235 offset:30720
	ds_read_b64_tr_b16 v[228:229], v235 offset:32256
	v_exp_f32_e32 v217, v217
	v_exp_f32_e32 v218, v218
	v_exp_f32_e32 v219, v219
	s_waitcnt lgkmcnt(9)
	v_mfma_f32_32x32x16_bf16 v[96:111], v[230:233], v[132:135], v[96:111]
	ds_read_b64_tr_b16 v[230:231], v235 offset:30784
	ds_read_b64_tr_b16 v[232:233], v235 offset:32320
	v_exp_f32_e32 v220, v220
	v_exp_f32_e32 v221, v221
	v_add_f32_e32 v179, v179, v214
	v_add_f32_e32 v202, v202, v215
	s_waitcnt lgkmcnt(10)
	v_mfma_f32_32x32x16_bf16 v[112:127], v[244:247], v[132:135], v[112:127]
	ds_read_b64_tr_b16 v[244:245], v235 offset:21504
	ds_read_b64_tr_b16 v[246:247], v235 offset:23040
	v_add_f32_e32 v179, v179, v216
	v_add_f32_e32 v202, v202, v217
	v_add_f32_e32 v179, v179, v218
	v_add_f32_e32 v202, v202, v219
	v_add_f32_e32 v179, v179, v220
	v_add_f32_e32 v202, v202, v221
	s_waitcnt lgkmcnt(11)
	v_mfma_f32_32x32x16_bf16 v[96:111], v[248:251], v[128:131], v[96:111]
	ds_read_b64_tr_b16 v[248:249], v235 offset:21568
	ds_read_b64_tr_b16 v[250:251], v235 offset:23104
	v_cvt_pk_bf16_f32 v210, v214, v215
	v_cvt_pk_bf16_f32 v211, v216, v217
	v_cvt_pk_bf16_f32 v212, v218, v219
	v_cvt_pk_bf16_f32 v213, v220, v221
	v_exp_f32_e32 v0, v0
	s_waitcnt lgkmcnt(12)
	v_mfma_f32_32x32x16_bf16 v[112:127], v[184:187], v[128:131], v[112:127]
	ds_read_b64_tr_b16 v[184:185], v235 offset:33792
	ds_read_b64_tr_b16 v[186:187], v235 offset:35328
	v_exp_f32_e32 v1, v1
	v_exp_f32_e32 v2, v2
	v_exp_f32_e32 v3, v3
	s_waitcnt lgkmcnt(12)
	v_mfma_f32_32x32x16_bf16 v[64:79], v[188:191], v[206:209], v[64:79]
	ds_read_b64_tr_b16 v[188:189], v235 offset:33856
	ds_read_b64_tr_b16 v[190:191], v235 offset:35392
	v_exp_f32_e32 v4, v4
	v_exp_f32_e32 v5, v5
	v_exp_f32_e32 v6, v6
	s_waitcnt lgkmcnt(12)
	v_mfma_f32_32x32x16_bf16 v[48:63], v[222:225], v[206:209], v[48:63]
	ds_read_b64_tr_b16 v[222:223], v235 offset:24576
	ds_read_b64_tr_b16 v[224:225], v235 offset:26112
	v_exp_f32_e32 v7, v7
	v_add_f32_e32 v179, v179, v0
	v_add_f32_e32 v202, v202, v1
	v_add_f32_e32 v179, v179, v2
	v_add_f32_e32 v202, v202, v3
	s_waitcnt lgkmcnt(12)
	v_mfma_f32_32x32x16_bf16 v[32:47], v[226:229], v[206:209], v[32:47]
	ds_read_b64_tr_b16 v[226:227], v235 offset:24640
	ds_read_b64_tr_b16 v[228:229], v235 offset:26176
	v_add_f32_e32 v179, v179, v4
	v_add_f32_e32 v202, v202, v5
	v_add_f32_e32 v179, v179, v6
	v_add_f32_e32 v202, v202, v7
	v_exp_f32_e32 v8, v8
	s_waitcnt lgkmcnt(12)
	v_mfma_f32_32x32x16_bf16 v[16:31], v[230:233], v[206:209], v[16:31]
	ds_read_b64_tr_b16 v[230:231], v235 offset:36864
	ds_read_b64_tr_b16 v[232:233], v235 offset:38400
	v_cvt_pk_bf16_f32 v214, v0, v1
	v_cvt_pk_bf16_f32 v215, v2, v3
	v_cvt_pk_bf16_f32 v216, v4, v5
	v_cvt_pk_bf16_f32 v217, v6, v7
	v_exp_f32_e32 v9, v9
	s_waitcnt lgkmcnt(12)
	v_mfma_f32_32x32x16_bf16 v[64:79], v[244:247], v[210:213], v[64:79]
	ds_read_b64_tr_b16 v[244:245], v235 offset:36928
	ds_read_b64_tr_b16 v[246:247], v235 offset:38464
	v_exp_f32_e32 v10, v10
	v_exp_f32_e32 v11, v11
	v_exp_f32_e32 v12, v12
	s_waitcnt lgkmcnt(12)
	v_mfma_f32_32x32x16_bf16 v[48:63], v[248:251], v[210:213], v[48:63]
	ds_read_b64_tr_b16 v[248:249], v235 offset:27648
	ds_read_b64_tr_b16 v[250:251], v235 offset:29184
	v_exp_f32_e32 v13, v13
	v_exp_f32_e32 v14, v14
	v_exp_f32_e32 v15, v15
	s_waitcnt lgkmcnt(12)
	v_mfma_f32_32x32x16_bf16 v[32:47], v[184:187], v[210:213], v[32:47]
	ds_read_b64_tr_b16 v[184:185], v235 offset:27712
	ds_read_b64_tr_b16 v[186:187], v235 offset:29248
	v_add_f32_e32 v179, v179, v8
	v_add_f32_e32 v202, v202, v9
	v_add_f32_e32 v179, v179, v10
	v_add_f32_e32 v202, v202, v11
	v_add_f32_e32 v179, v179, v12
	v_add_f32_e32 v202, v202, v13
	s_waitcnt lgkmcnt(12)
	v_mfma_f32_32x32x16_bf16 v[16:31], v[188:191], v[210:213], v[16:31]
	ds_read_b64_tr_b16 v[188:189], v235 offset:39936
	ds_read_b64_tr_b16 v[190:191], v235 offset:41472
	v_add_f32_e32 v179, v179, v14
	v_add_f32_e32 v202, v202, v15
	v_cvt_pk_bf16_f32 v218, v8, v9
	v_cvt_pk_bf16_f32 v219, v10, v11
	v_cvt_pk_bf16_f32 v220, v12, v13
	v_cvt_pk_bf16_f32 v221, v14, v15
	s_waitcnt lgkmcnt(12)
	v_mfma_f32_32x32x16_bf16 v[64:79], v[222:225], v[214:217], v[64:79]
	ds_read_b64_tr_b16 v[222:223], v235 offset:40000
	ds_read_b64_tr_b16 v[224:225], v235 offset:41536
	v_max3_f32 v243, v96, v97, v98
	v_max3_f32 v239, v112, v113, v114
	v_max3_f32 v243, v243, v99, v100
	v_max3_f32 v239, v239, v115, v116
	v_max3_f32 v243, v243, v101, v102
	s_waitcnt lgkmcnt(12)
	v_mfma_f32_32x32x16_bf16 v[48:63], v[226:229], v[214:217], v[48:63]
	v_max3_f32 v239, v239, v117, v118
	v_max3_f32 v243, v243, v103, v104
	v_max3_f32 v239, v239, v119, v120
	v_max3_f32 v243, v243, v105, v106
	v_max3_f32 v239, v239, v121, v122
	v_max3_f32 v243, v243, v107, v108
	s_waitcnt lgkmcnt(10)
	v_mfma_f32_32x32x16_bf16 v[32:47], v[230:233], v[214:217], v[32:47]
	v_max3_f32 v239, v239, v123, v124
	v_max3_f32 v243, v243, v109, v110
	v_max3_f32 v239, v239, v125, v126
	v_max_f32_e32 v243, v243, v111
	v_max_f32_e32 v239, v239, v127
	v_max_f32_e32 v243, v243, v239
	s_waitcnt lgkmcnt(8)
	v_mfma_f32_32x32x16_bf16 v[16:31], v[244:247], v[214:217], v[16:31]
	s_waitcnt vmcnt(0)
	v_add3_u32 v238, s38, v178, v160
	v_add3_u32 v239, s38, v180, v160
	ds_write_b128 v238, v[156:159]
	ds_write_b128 v238, v[152:155] offset:9216
	s_waitcnt lgkmcnt(8)
	v_mfma_f32_32x32x16_bf16 v[64:79], v[248:251], v[218:221], v[64:79]
	ds_write_b128 v239, v[148:151] offset:18432
	ds_write_b128 v239, v[144:147] offset:30720
	v_mov_b32_e32 v239, v243
	s_min_i32 s0, s31, 0xf80
	v_add_u32_e32 v238, s0, v181
	v_min_i32_e32 v238, 0x100f, v238
	s_waitcnt lgkmcnt(8)
	v_mfma_f32_32x32x16_bf16 v[48:63], v[184:187], v[218:221], v[48:63]
	v_permlane32_swap_b32_e32 v243, v239
	v_mad_i64_i32 v[192:193], s[0:1], v238, s51, v[162:163]
	global_load_dwordx4 v[156:159], v[192:193], off offset:1024
	global_load_dwordx4 v[152:155], v[192:193], off offset:1152
	s_waitcnt lgkmcnt(6)
	v_mfma_f32_32x32x16_bf16 v[32:47], v[188:191], v[218:221], v[32:47]
	global_load_dwordx4 v[148:151], v[192:193], off offset:2048
	global_load_dwordx4 v[144:147], v[192:193], off offset:2176
	v_max_f32_e32 v243, v243, v239
	s_waitcnt lgkmcnt(4)
	v_mfma_f32_32x32x16_bf16 v[16:31], v[222:225], v[218:221], v[16:31]
	s_mov_b32 s39, s30
	s_mov_b32 s26, s29
	s_mov_b32 s29, s38
	s_add_i32 s0, s38, 0xa800
	s_cmp_lg_u32 s0, 0x1f800
	s_cselect_b32 s38, s0, 0
	s_mov_b32 s35, s31
	v_cmp_lt_f32_e32 vcc, s10, v243
	s_cbranch_vccz .Latt1_e_noresc
; #define A_ISSUE(t) do { int tok_ = 64 * (t) + lrow; tok_ = tok_ > LT - 1 ? LT - 1 : tok_; const bf16_t* src_ = pb + (size_t)tok_ * INC; \
;         pre[0] = *(const u32x4*)(src_ + 512); pre[1] = *(const u32x4*)(src_ + 576); pre[2] = *(const u32x4*)(src_ + 1024); pre[3] = *(const u32x4*)(src_ + 1088); } while (0)
; #define A_WRITE(bufo) do { LAS char* d_ = lds + (bufo); \
;         *(LAS u32x4*)(d_ + lrow * AKP + lch * 16) = pre[0]; *(LAS u32x4*)(d_ + AKS + lrow * AKP + lch * 16) = pre[1]; \
;         *(LAS u32x4*)(d_ + 2 * AKS + lrow * AVP + lch * 16) = pre[2]; *(LAS u32x4*)(d_ + 2 * AKS + AVS + lrow * AVP + lch * 16) = pre[3]; } while (0)
; __device__ __forceinline__ void attn_unit_A(const AttnP& P, int u, LAS char* lds) {
;     ...
;     for (int t = 0; t < nt; ++t) {
;         const bool more = (t + 1 < nt);
;         if (more) { A_WRITE(bnext); if (t + 2 < nt) A_ISSUE(t + 2); }
;         int clsn = clsk;
;         if (more) { clsn = A_CLS(t + 1);
;             if (clsn != clsk) { const float dc = A_CVAL(clsn) - A_CVAL(clsk); clsk = clsn;
; #pragma unroll
;                 for (int r = 0; r < 16; ++r) negc[r] += dc; } }
;     ...
;         if (more) {
;             if (clsn == 1) A_NEAR(sa0, sa1, t + 1);
;             float mx_; A_ROWMAX(sa0, sa1, mx_);
;             if (__any(mx_ > 8.0f)) { const float dl = fmaxf(mx_, 0.f); const float f_ = __builtin_amdgcn_exp2f(-dl); lrun *= f_;
; #pragma unroll
;                 for (int r = 0; r < 16; ++r) { sa0[r] -= dl; sa1[r] -= dl; negc[r] -= dl; }
; #pragma unroll
;                 for (int d = 0; d < 4; ++d)
; #pragma unroll
;                     for (int r = 0; r < 16; ++r) o[d][r] *= f_; }
;         }
;         bcur = bnext; bnext = bnext + ABUF; if (bnext == 3 * ABUF) bnext = 0;
	s_nop 11
	v_max_f32_e32 v243, 0, v243
	v_exp_f32_e64 v192, -v243
	v_sub_f32_e32 v80, v80, v243
	v_sub_f32_e32 v81, v81, v243
	v_sub_f32_e32 v82, v82, v243
	v_sub_f32_e32 v83, v83, v243
	v_sub_f32_e32 v84, v84, v243
	v_sub_f32_e32 v85, v85, v243
	v_sub_f32_e32 v86, v86, v243
	v_sub_f32_e32 v87, v87, v243
	v_sub_f32_e32 v88, v88, v243
	v_sub_f32_e32 v89, v89, v243
	v_sub_f32_e32 v90, v90, v243
	v_sub_f32_e32 v91, v91, v243
	v_sub_f32_e32 v92, v92, v243
	v_sub_f32_e32 v93, v93, v243
	v_sub_f32_e32 v94, v94, v243
	v_sub_f32_e32 v95, v95, v243
	v_sub_f32_e32 v96, v96, v243
	v_sub_f32_e32 v97, v97, v243
	v_sub_f32_e32 v98, v98, v243
	v_sub_f32_e32 v99, v99, v243
	v_sub_f32_e32 v100, v100, v243
	v_sub_f32_e32 v101, v101, v243
	v_sub_f32_e32 v102, v102, v243
	v_sub_f32_e32 v103, v103, v243
	v_sub_f32_e32 v104, v104, v243
	v_sub_f32_e32 v105, v105, v243
	v_sub_f32_e32 v106, v106, v243
	v_sub_f32_e32 v107, v107, v243
	v_sub_f32_e32 v108, v108, v243
	v_sub_f32_e32 v109, v109, v243
	v_sub_f32_e32 v110, v110, v243
	v_sub_f32_e32 v111, v111, v243
	v_sub_f32_e32 v112, v112, v243
	v_sub_f32_e32 v113, v113, v243
	v_sub_f32_e32 v114, v114, v243
	v_sub_f32_e32 v115, v115, v243
	v_sub_f32_e32 v116, v116, v243
	v_sub_f32_e32 v117, v117, v243
	v_sub_f32_e32 v118, v118, v243
	v_sub_f32_e32 v119, v119, v243
	v_sub_f32_e32 v120, v120, v243
	v_sub_f32_e32 v121, v121, v243
	v_sub_f32_e32 v122, v122, v243
	v_sub_f32_e32 v123, v123, v243
	v_sub_f32_e32 v124, v124, v243
	v_sub_f32_e32 v125, v125, v243
	v_sub_f32_e32 v126, v126, v243
	v_sub_f32_e32 v127, v127, v243
	v_pk_mul_f32 v[64:65], v[64:65], v[192:193] op_sel_hi:[1,0]
	v_pk_mul_f32 v[66:67], v[66:67], v[192:193] op_sel_hi:[1,0]
	v_pk_mul_f32 v[68:69], v[68:69], v[192:193] op_sel_hi:[1,0]
	v_pk_mul_f32 v[70:71], v[70:71], v[192:193] op_sel_hi:[1,0]
	v_pk_mul_f32 v[72:73], v[72:73], v[192:193] op_sel_hi:[1,0]
	v_pk_mul_f32 v[74:75], v[74:75], v[192:193] op_sel_hi:[1,0]
	v_pk_mul_f32 v[76:77], v[76:77], v[192:193] op_sel_hi:[1,0]
	v_pk_mul_f32 v[78:79], v[78:79], v[192:193] op_sel_hi:[1,0]
	v_pk_mul_f32 v[48:49], v[48:49], v[192:193] op_sel_hi:[1,0]
	v_pk_mul_f32 v[50:51], v[50:51], v[192:193] op_sel_hi:[1,0]
	v_pk_mul_f32 v[52:53], v[52:53], v[192:193] op_sel_hi:[1,0]
	v_pk_mul_f32 v[54:55], v[54:55], v[192:193] op_sel_hi:[1,0]
	v_pk_mul_f32 v[56:57], v[56:57], v[192:193] op_sel_hi:[1,0]
	v_pk_mul_f32 v[58:59], v[58:59], v[192:193] op_sel_hi:[1,0]
	v_pk_mul_f32 v[60:61], v[60:61], v[192:193] op_sel_hi:[1,0]
	v_pk_mul_f32 v[62:63], v[62:63], v[192:193] op_sel_hi:[1,0]
	v_pk_mul_f32 v[32:33], v[32:33], v[192:193] op_sel_hi:[1,0]
	v_pk_mul_f32 v[34:35], v[34:35], v[192:193] op_sel_hi:[1,0]
	v_pk_mul_f32 v[36:37], v[36:37], v[192:193] op_sel_hi:[1,0]
	v_pk_mul_f32 v[38:39], v[38:39], v[192:193] op_sel_hi:[1,0]
	v_pk_mul_f32 v[40:41], v[40:41], v[192:193] op_sel_hi:[1,0]
	v_pk_mul_f32 v[42:43], v[42:43], v[192:193] op_sel_hi:[1,0]
	v_pk_mul_f32 v[44:45], v[44:45], v[192:193] op_sel_hi:[1,0]
	v_pk_mul_f32 v[46:47], v[46:47], v[192:193] op_sel_hi:[1,0]
	v_pk_mul_f32 v[16:17], v[16:17], v[192:193] op_sel_hi:[1,0]
	v_pk_mul_f32 v[18:19], v[18:19], v[192:193] op_sel_hi:[1,0]
	v_pk_mul_f32 v[20:21], v[20:21], v[192:193] op_sel_hi:[1,0]
	v_pk_mul_f32 v[22:23], v[22:23], v[192:193] op_sel_hi:[1,0]
	v_pk_mul_f32 v[24:25], v[24:25], v[192:193] op_sel_hi:[1,0]
	v_pk_mul_f32 v[26:27], v[26:27], v[192:193] op_sel_hi:[1,0]
	v_pk_mul_f32 v[28:29], v[28:29], v[192:193] op_sel_hi:[1,0]
	v_pk_mul_f32 v[30:31], v[30:31], v[192:193] op_sel_hi:[1,0]
	v_mul_f32_e32 v179, v179, v192
	v_mul_f32_e32 v202, v202, v192
	s_nop 1
.Latt1_e_noresc:
	s_waitcnt lgkmcnt(0)
	s_barrier
	s_cmpk_eq_i32 s35, 0xfc0
	s_cbranch_scc1 .Latt1_exit
	s_add_i32 s0, s28, s35
	s_add_i32 s31, s35, 64
	s_add_i32 s0, s0, 33
	s_cmpk_gt_i32 s0, 0x7f
	s_cselect_b32 s0, 2, 1
	s_cmp_gt_i32 s31, s16
	s_cselect_b32 s30, s0, 0
	s_cmp_eq_u32 s30, s39
	s_cbranch_scc1 .Latt1_o_same
	s_cmp_eq_u32 s30, 2
	s_cselect_b32 s0, 1, 0
	s_lshl_b32 s0, s0, 10
	s_add_i32 s0, s0, 0x1f800
	s_cmp_eq_u32 s39, 2
	s_cselect_b32 s1, 1, 0
	s_lshl_b32 s1, s1, 10
	s_add_i32 s1, s1, 0x1f800
	v_mov_b32_e32 v238, s0
	v_mov_b32_e32 v239, s1
	ds_read_b32 v238, v238
	ds_read_b32 v239, v239
	s_cmp_eq_u32 s30, 1
	s_cselect_b32 s0, 0, 0x3f800000
	s_cmp_eq_u32 s39, 1
	s_cselect_b32 s1, 0, 0x3f800000
	s_waitcnt lgkmcnt(0)
	v_mul_f32_e32 v238, s0, v238
	v_mul_f32_e32 v239, s1, v239
	v_sub_f32_e32 v238, v238, v239
	v_add_f32_e32 v80, v80, v238
	v_add_f32_e32 v81, v81, v238
	v_add_f32_e32 v82, v82, v238
	v_add_f32_e32 v83, v83, v238
	v_add_f32_e32 v84, v84, v238
	v_add_f32_e32 v85, v85, v238
	v_add_f32_e32 v86, v86, v238
	v_add_f32_e32 v87, v87, v238
	v_add_f32_e32 v88, v88, v238
	v_add_f32_e32 v89, v89, v238
	v_add_f32_e32 v90, v90, v238
	v_add_f32_e32 v91, v91, v238
	v_add_f32_e32 v92, v92, v238
	v_add_f32_e32 v93, v93, v238
	v_add_f32_e32 v94, v94, v238
	v_add_f32_e32 v95, v95, v238
.Latt1_o_same:
	v_add_u32_e32 v203, s29, v174
	v_add_u32_e32 v235, s26, v182
	s_cmp_eq_u32 s30, 1
	s_cbranch_scc1 .Latt1_o_near
	ds_read_b128 v[184:187], v203
	ds_read_b128 v[188:191], v203 offset:4608
	ds_read_b128 v[222:225], v203 offset:32
	ds_read_b128 v[226:229], v203 offset:4640
	ds_read_b128 v[230:233], v203 offset:64
	ds_read_b128 v[244:247], v203 offset:4672
	ds_read_b128 v[248:251], v203 offset:96
	v_exp_f32_e32 v96, v96
	v_exp_f32_e32 v97, v97
	v_exp_f32_e32 v98, v98
	v_exp_f32_e32 v99, v99
	v_exp_f32_e32 v100, v100
	v_exp_f32_e32 v101, v101
	v_exp_f32_e32 v102, v102
	v_exp_f32_e32 v103, v103
	s_waitcnt lgkmcnt(6)
	v_mfma_f32_32x32x16_bf16 v[206:221], v[184:187], v[140:143], v[80:95]
	ds_read_b128 v[184:187], v203 offset:4704
	v_add_f32_e32 v179, v179, v96
	v_add_f32_e32 v202, v202, v97
	v_add_f32_e32 v179, v179, v98
	v_add_f32_e32 v202, v202, v99
	v_exp_f32_e32 v104, v104
	s_waitcnt lgkmcnt(6)
	v_mfma_f32_32x32x16_bf16 v[0:15], v[188:191], v[140:143], v[80:95]
	ds_read_b64_tr_b16 v[188:189], v235 offset:18432
	ds_read_b64_tr_b16 v[190:191], v235 offset:19968
	v_add_f32_e32 v179, v179, v100
	v_add_f32_e32 v202, v202, v101
	v_add_f32_e32 v179, v179, v102
	v_add_f32_e32 v202, v202, v103
	v_exp_f32_e32 v105, v105
	s_branch .Latt1_o_join
; #define LAS __attribute__((address_space(3)))
; #define A_VLOAD(dst, d) do { const LAS char* vb_ = vbase + ((d) >> 1) * AVS + ((d) & 1) * 64; \
;         _Pragma("unroll") for (int ks = 0; ks < 4; ++ks) { const s16x4 vl_ = vtr(vb_ + (16 * ks) * AVP), vh_ = vtr(vb_ + (16 * ks + 8) * AVP); \
;             dst[ks] = (bf16x8){vl_[0], vl_[1], vl_[2], vl_[3], vh_[0], vh_[1], vh_[2], vh_[3]}; } } while (0)
; __device__ __forceinline__ void attn_unit_A(const AttnP& P, int u, LAS char* lds) {
;     ...
;         const LAS char* vbase = lds + bcur + 2 * AKS + vrow * AVP + vcolb;
;     ...
;         bf16x8 vfa[4], vfb[4];
;         A_VLOAD(vfa, 0);
;         __builtin_amdgcn_sched_barrier(0);
;         float sacc = 0.f;
; #pragma unroll
;         for (int r = 0; r < 16; ++r) { sa0[r] = __builtin_amdgcn_exp2f(sa0[r]); sa1[r] = __builtin_amdgcn_exp2f(sa1[r]); sacc += sa0[r] + sa1[r]; }
.Latt1_o_near:
	v_add_u32_e32 v238, s35, v183
	s_add_i32 s0, 0, 0x1f800
	v_add_u32_e32 v206, 0x40, v238
	v_med3_i32 v206, v206, s87, v240
	v_lshl_add_u32 v206, v206, 2, s0
	v_add_u32_e32 v207, 0x41, v238
	v_med3_i32 v207, v207, s87, v240
	v_lshl_add_u32 v207, v207, 2, s0
	v_add_u32_e32 v208, 0x42, v238
	v_med3_i32 v208, v208, s87, v240
	v_lshl_add_u32 v208, v208, 2, s0
	v_add_u32_e32 v209, 0x43, v238
	v_med3_i32 v209, v209, s87, v240
	v_lshl_add_u32 v209, v209, 2, s0
	v_add_u32_e32 v210, 0x48, v238
	v_med3_i32 v210, v210, s87, v240
	v_lshl_add_u32 v210, v210, 2, s0
	v_add_u32_e32 v211, 0x49, v238
	v_med3_i32 v211, v211, s87, v240
	v_lshl_add_u32 v211, v211, 2, s0
	v_add_u32_e32 v212, 0x4a, v238
	v_med3_i32 v212, v212, s87, v240
	v_lshl_add_u32 v212, v212, 2, s0
	v_add_u32_e32 v213, 0x4b, v238
	v_med3_i32 v213, v213, s87, v240
	v_lshl_add_u32 v213, v213, 2, s0
	v_add_u32_e32 v214, 0x50, v238
	v_med3_i32 v214, v214, s87, v240
	v_lshl_add_u32 v214, v214, 2, s0
	v_add_u32_e32 v215, 0x51, v238
	v_med3_i32 v215, v215, s87, v240
	v_lshl_add_u32 v215, v215, 2, s0
	v_add_u32_e32 v216, 0x52, v238
	v_med3_i32 v216, v216, s87, v240
	v_lshl_add_u32 v216, v216, 2, s0
	v_add_u32_e32 v217, 0x53, v238
	v_med3_i32 v217, v217, s87, v240
	v_lshl_add_u32 v217, v217, 2, s0
	v_add_u32_e32 v218, 0x58, v238
	v_med3_i32 v218, v218, s87, v240
	v_lshl_add_u32 v218, v218, 2, s0
	v_add_u32_e32 v219, 0x59, v238
	v_med3_i32 v219, v219, s87, v240
	v_lshl_add_u32 v219, v219, 2, s0
	v_add_u32_e32 v220, 0x5a, v238
	v_med3_i32 v220, v220, s87, v240
	v_lshl_add_u32 v220, v220, 2, s0
	v_add_u32_e32 v221, 0x5b, v238
	v_med3_i32 v221, v221, s87, v240
	v_lshl_add_u32 v221, v221, 2, s0
	ds_read_b32 v206, v206 offset:512
	ds_read_b32 v207, v207 offset:512
	ds_read_b32 v208, v208 offset:512
	ds_read_b32 v209, v209 offset:512
	ds_read_b32 v210, v210 offset:512
	ds_read_b32 v211, v211 offset:512
	ds_read_b32 v212, v212 offset:512
	ds_read_b32 v213, v213 offset:512
	ds_read_b32 v214, v214 offset:512
	ds_read_b32 v215, v215 offset:512
	ds_read_b32 v216, v216 offset:512
	ds_read_b32 v217, v217 offset:512
	ds_read_b32 v218, v218 offset:512
	ds_read_b32 v219, v219 offset:512
	ds_read_b32 v220, v220 offset:512
	ds_read_b32 v221, v221 offset:512
	v_add_u32_e32 v0, 0x60, v238
	v_med3_i32 v0, v0, s87, v240
	v_lshl_add_u32 v0, v0, 2, s0
	v_add_u32_e32 v1, 0x61, v238
	v_med3_i32 v1, v1, s87, v240
	v_lshl_add_u32 v1, v1, 2, s0
	v_add_u32_e32 v2, 0x62, v238
	v_med3_i32 v2, v2, s87, v240
	v_lshl_add_u32 v2, v2, 2, s0
	v_add_u32_e32 v3, 0x63, v238
	v_med3_i32 v3, v3, s87, v240
	v_lshl_add_u32 v3, v3, 2, s0
	v_add_u32_e32 v4, 0x68, v238
	v_med3_i32 v4, v4, s87, v240
	v_lshl_add_u32 v4, v4, 2, s0
	v_add_u32_e32 v5, 0x69, v238
	v_med3_i32 v5, v5, s87, v240
	v_lshl_add_u32 v5, v5, 2, s0
	v_add_u32_e32 v6, 0x6a, v238
	v_med3_i32 v6, v6, s87, v240
	v_lshl_add_u32 v6, v6, 2, s0
	v_add_u32_e32 v7, 0x6b, v238
	v_med3_i32 v7, v7, s87, v240
	v_lshl_add_u32 v7, v7, 2, s0
	v_add_u32_e32 v8, 0x70, v238
	v_med3_i32 v8, v8, s87, v240
	v_lshl_add_u32 v8, v8, 2, s0
	v_add_u32_e32 v9, 0x71, v238
	v_med3_i32 v9, v9, s87, v240
	v_lshl_add_u32 v9, v9, 2, s0
	v_add_u32_e32 v10, 0x72, v238
	v_med3_i32 v10, v10, s87, v240
	v_lshl_add_u32 v10, v10, 2, s0
	v_add_u32_e32 v11, 0x73, v238
	v_med3_i32 v11, v11, s87, v240
	v_lshl_add_u32 v11, v11, 2, s0
	v_add_u32_e32 v12, 0x78, v238
	v_med3_i32 v12, v12, s87, v240
	v_lshl_add_u32 v12, v12, 2, s0
	v_add_u32_e32 v13, 0x79, v238
	v_med3_i32 v13, v13, s87, v240
	v_lshl_add_u32 v13, v13, 2, s0
	v_add_u32_e32 v14, 0x7a, v238
	v_med3_i32 v14, v14, s87, v240
	v_lshl_add_u32 v14, v14, 2, s0
	v_add_u32_e32 v15, 0x7b, v238
	v_med3_i32 v15, v15, s87, v240
	v_lshl_add_u32 v15, v15, 2, s0
	ds_read_b32 v0, v0 offset:512
	ds_read_b32 v1, v1 offset:512
	ds_read_b32 v2, v2 offset:512
	ds_read_b32 v3, v3 offset:512
	ds_read_b32 v4, v4 offset:512
	ds_read_b32 v5, v5 offset:512
	ds_read_b32 v6, v6 offset:512
	ds_read_b32 v7, v7 offset:512
	ds_read_b32 v8, v8 offset:512
	ds_read_b32 v9, v9 offset:512
	ds_read_b32 v10, v10 offset:512
	ds_read_b32 v11, v11 offset:512
	ds_read_b32 v12, v12 offset:512
	ds_read_b32 v13, v13 offset:512
	ds_read_b32 v14, v14 offset:512
	ds_read_b32 v15, v15 offset:512
	s_waitcnt lgkmcnt(0)
	v_add_f32_e32 v206, v206, v80
	v_add_f32_e32 v207, v207, v80
	v_add_f32_e32 v208, v208, v80
	v_add_f32_e32 v209, v209, v80
	v_add_f32_e32 v210, v210, v80
	v_add_f32_e32 v211, v211, v80
	v_add_f32_e32 v212, v212, v80
	v_add_f32_e32 v213, v213, v80
	v_add_f32_e32 v214, v214, v80
	v_add_f32_e32 v215, v215, v80
	v_add_f32_e32 v216, v216, v80
	v_add_f32_e32 v217, v217, v80
	v_add_f32_e32 v218, v218, v80
	v_add_f32_e32 v219, v219, v80
	v_add_f32_e32 v220, v220, v80
	v_add_f32_e32 v221, v221, v80
	v_add_f32_e32 v0, v0, v80
	v_add_f32_e32 v1, v1, v80
	v_add_f32_e32 v2, v2, v80
	v_add_f32_e32 v3, v3, v80
	v_add_f32_e32 v4, v4, v80
	v_add_f32_e32 v5, v5, v80
	v_add_f32_e32 v6, v6, v80
	v_add_f32_e32 v7, v7, v80
	v_add_f32_e32 v8, v8, v80
	v_add_f32_e32 v9, v9, v80
	v_add_f32_e32 v10, v10, v80
	v_add_f32_e32 v11, v11, v80
	v_add_f32_e32 v12, v12, v80
	v_add_f32_e32 v13, v13, v80
	v_add_f32_e32 v14, v14, v80
	v_add_f32_e32 v15, v15, v80
	ds_read_b128 v[184:187], v203
	ds_read_b128 v[188:191], v203 offset:4608
	ds_read_b128 v[222:225], v203 offset:32
	ds_read_b128 v[226:229], v203 offset:4640
	ds_read_b128 v[230:233], v203 offset:64
	ds_read_b128 v[244:247], v203 offset:4672
	ds_read_b128 v[248:251], v203 offset:96
	v_exp_f32_e32 v96, v96
	v_exp_f32_e32 v97, v97
	v_exp_f32_e32 v98, v98
	v_exp_f32_e32 v99, v99
	v_exp_f32_e32 v100, v100
	v_exp_f32_e32 v101, v101
	v_exp_f32_e32 v102, v102
	v_exp_f32_e32 v103, v103
	s_waitcnt lgkmcnt(6)
	v_mfma_f32_32x32x16_bf16 v[206:221], v[184:187], v[140:143], v[206:221]
	ds_read_b128 v[184:187], v203 offset:4704
	v_add_f32_e32 v179, v179, v96
	v_add_f32_e32 v202, v202, v97
	v_add_f32_e32 v179, v179, v98
	v_add_f32_e32 v202, v202, v99
	v_exp_f32_e32 v104, v104
	s_waitcnt lgkmcnt(6)
	v_mfma_f32_32x32x16_bf16 v[0:15], v[188:191], v[140:143], v[0:15]
	ds_read_b64_tr_b16 v[188:189], v235 offset:18432
	ds_read_b64_tr_b16 v[190:191], v235 offset:19968
	v_add_f32_e32 v179, v179, v100
	v_add_f32_e32 v202, v202, v101
	v_add_f32_e32 v179, v179, v102
	v_add_f32_e32 v202, v202, v103
	v_exp_f32_e32 v105, v105
; #define LAS __attribute__((address_space(3)))
; __device__ __forceinline__ void attn_unit_A(const AttnP& P, int u, LAS char* lds) {
;     ...
;         const LAS char* vbase = lds + bcur + 2 * AKS + vrow * AVP + vcolb;
;     ...
;         bf16x8 vfa[4], vfb[4];
;         A_VLOAD(vfa, 0);
;         __builtin_amdgcn_sched_barrier(0);
;         float sacc = 0.f;
; #pragma unroll
;         for (int r = 0; r < 16; ++r) { sa0[r] = __builtin_amdgcn_exp2f(sa0[r]); sa1[r] = __builtin_amdgcn_exp2f(sa1[r]); sacc += sa0[r] + sa1[r]; }
;         lrun += sacc;
;         bf16x8 pf[4];
;         { u32x4 a;
;           a.x = cvtpk(sa0[0], sa0[1]); a.y = cvtpk(sa0[2], sa0[3]); a.z = cvtpk(sa0[4], sa0[5]); a.w = cvtpk(sa0[6], sa0[7]); pf[0] = __builtin_bit_cast(bf16x8, a);
;           a.x = cvtpk(sa0[8], sa0[9]); a.y = cvtpk(sa0[10], sa0[11]); a.z = cvtpk(sa0[12], sa0[13]); a.w = cvtpk(sa0[14], sa0[15]); pf[1] = __builtin_bit_cast(bf16x8, a);
;           a.x = cvtpk(sa1[0], sa1[1]); a.y = cvtpk(sa1[2], sa1[3]); a.z = cvtpk(sa1[4], sa1[5]); a.w = cvtpk(sa1[6], sa1[7]); pf[2] = __builtin_bit_cast(bf16x8, a);
;           a.x = cvtpk(sa1[8], sa1[9]); a.y = cvtpk(sa1[10], sa1[11]); a.z = cvtpk(sa1[12], sa1[13]); a.w = cvtpk(sa1[14], sa1[15]); pf[3] = __builtin_bit_cast(bf16x8, a); }
;         __builtin_amdgcn_sched_barrier(0);
;         A_VLOAD(vfb, 1);
;         __builtin_amdgcn_sched_barrier(0);
;         A_VMMA(vfa, 0);
;         A_VLOAD(vfa, 2);
;         __builtin_amdgcn_sched_barrier(0);
;         A_VMMA(vfb, 1);
;         A_VLOAD(vfb, 3);
;         __builtin_amdgcn_sched_barrier(0);
;         A_VMMA(vfa, 2);
;         __builtin_amdgcn_sched_barrier(0);
;         A_VMMA(vfb, 3);
;     ...
;         __builtin_amdgcn_sched_barrier(0); A_BAR(); A_QKBLK();
;     ...
;         if (more) {
;             if (clsn == 1) A_NEAR(sa0, sa1, t + 1);
;             float mx_; A_ROWMAX(sa0, sa1, mx_);
;             if (__any(mx_ > 8.0f)) { const float dl = fmaxf(mx_, 0.f); const float f_ = __builtin_amdgcn_exp2f(-dl); lrun *= f_;
; #pragma unroll
;                 for (int r = 0; r < 16; ++r) { sa0[r] -= dl; sa1[r] -= dl; negc[r] -= dl; }
; #pragma unroll
;                 for (int d = 0; d < 4; ++d)
; #pragma unroll
;                     for (int r = 0; r < 16; ++r) o[d][r] *= f_; }
;         }
;         bcur = bnext; bnext = bnext + ABUF; if (bnext == 3 * ABUF) bnext = 0;
.Latt1_o_join:
	s_waitcnt lgkmcnt(7)
	v_mfma_f32_32x32x16_bf16 v[206:221], v[222:225], v[136:139], v[206:221]
	ds_read_b64_tr_b16 v[222:223], v235 offset:18496
	ds_read_b64_tr_b16 v[224:225], v235 offset:20032
	v_cvt_pk_bf16_f32 v96, v96, v97
	v_cvt_pk_bf16_f32 v97, v98, v99
	v_cvt_pk_bf16_f32 v98, v100, v101
	v_cvt_pk_bf16_f32 v99, v102, v103
	v_exp_f32_e32 v106, v106
	s_waitcnt lgkmcnt(8)
	v_mfma_f32_32x32x16_bf16 v[0:15], v[226:229], v[136:139], v[0:15]
	ds_read_b64_tr_b16 v[226:227], v235 offset:30720
	ds_read_b64_tr_b16 v[228:229], v235 offset:32256
	v_exp_f32_e32 v107, v107
	v_exp_f32_e32 v108, v108
	v_exp_f32_e32 v109, v109
	s_waitcnt lgkmcnt(9)
	v_mfma_f32_32x32x16_bf16 v[206:221], v[230:233], v[132:135], v[206:221]
	ds_read_b64_tr_b16 v[230:231], v235 offset:30784
	ds_read_b64_tr_b16 v[232:233], v235 offset:32320
	v_exp_f32_e32 v110, v110
	v_exp_f32_e32 v111, v111
	v_add_f32_e32 v179, v179, v104
	v_add_f32_e32 v202, v202, v105
	s_waitcnt lgkmcnt(10)
	v_mfma_f32_32x32x16_bf16 v[0:15], v[244:247], v[132:135], v[0:15]
	ds_read_b64_tr_b16 v[244:245], v235 offset:21504
	ds_read_b64_tr_b16 v[246:247], v235 offset:23040
	v_add_f32_e32 v179, v179, v106
	v_add_f32_e32 v202, v202, v107
	v_add_f32_e32 v179, v179, v108
	v_add_f32_e32 v202, v202, v109
	v_add_f32_e32 v179, v179, v110
	v_add_f32_e32 v202, v202, v111
	s_waitcnt lgkmcnt(11)
	v_mfma_f32_32x32x16_bf16 v[206:221], v[248:251], v[128:131], v[206:221]
	ds_read_b64_tr_b16 v[248:249], v235 offset:21568
	ds_read_b64_tr_b16 v[250:251], v235 offset:23104
	v_cvt_pk_bf16_f32 v100, v104, v105
	v_cvt_pk_bf16_f32 v101, v106, v107
	v_cvt_pk_bf16_f32 v102, v108, v109
	v_cvt_pk_bf16_f32 v103, v110, v111
	v_exp_f32_e32 v112, v112
	s_waitcnt lgkmcnt(12)
	v_mfma_f32_32x32x16_bf16 v[0:15], v[184:187], v[128:131], v[0:15]
	ds_read_b64_tr_b16 v[184:185], v235 offset:33792
	ds_read_b64_tr_b16 v[186:187], v235 offset:35328
	v_exp_f32_e32 v113, v113
	v_exp_f32_e32 v114, v114
	v_exp_f32_e32 v115, v115
	s_waitcnt lgkmcnt(12)
	v_mfma_f32_32x32x16_bf16 v[64:79], v[188:191], v[96:99], v[64:79]
	ds_read_b64_tr_b16 v[188:189], v235 offset:33856
	ds_read_b64_tr_b16 v[190:191], v235 offset:35392
	v_exp_f32_e32 v116, v116
	v_exp_f32_e32 v117, v117
	v_exp_f32_e32 v118, v118
	s_waitcnt lgkmcnt(12)
	v_mfma_f32_32x32x16_bf16 v[48:63], v[222:225], v[96:99], v[48:63]
	ds_read_b64_tr_b16 v[222:223], v235 offset:24576
	ds_read_b64_tr_b16 v[224:225], v235 offset:26112
	v_exp_f32_e32 v119, v119
	v_add_f32_e32 v179, v179, v112
	v_add_f32_e32 v202, v202, v113
	v_add_f32_e32 v179, v179, v114
	v_add_f32_e32 v202, v202, v115
	s_waitcnt lgkmcnt(12)
	v_mfma_f32_32x32x16_bf16 v[32:47], v[226:229], v[96:99], v[32:47]
	ds_read_b64_tr_b16 v[226:227], v235 offset:24640
	ds_read_b64_tr_b16 v[228:229], v235 offset:26176
	v_add_f32_e32 v179, v179, v116
	v_add_f32_e32 v202, v202, v117
	v_add_f32_e32 v179, v179, v118
	v_add_f32_e32 v202, v202, v119
	v_exp_f32_e32 v120, v120
	s_waitcnt lgkmcnt(12)
	v_mfma_f32_32x32x16_bf16 v[16:31], v[230:233], v[96:99], v[16:31]
	ds_read_b64_tr_b16 v[230:231], v235 offset:36864
	ds_read_b64_tr_b16 v[232:233], v235 offset:38400
	v_cvt_pk_bf16_f32 v104, v112, v113
	v_cvt_pk_bf16_f32 v105, v114, v115
	v_cvt_pk_bf16_f32 v106, v116, v117
	v_cvt_pk_bf16_f32 v107, v118, v119
	v_exp_f32_e32 v121, v121
	s_waitcnt lgkmcnt(12)
	v_mfma_f32_32x32x16_bf16 v[64:79], v[244:247], v[100:103], v[64:79]
	ds_read_b64_tr_b16 v[244:245], v235 offset:36928
	ds_read_b64_tr_b16 v[246:247], v235 offset:38464
	v_exp_f32_e32 v122, v122
	v_exp_f32_e32 v123, v123
	v_exp_f32_e32 v124, v124
	s_waitcnt lgkmcnt(12)
	v_mfma_f32_32x32x16_bf16 v[48:63], v[248:251], v[100:103], v[48:63]
	ds_read_b64_tr_b16 v[248:249], v235 offset:27648
	ds_read_b64_tr_b16 v[250:251], v235 offset:29184
	v_exp_f32_e32 v125, v125
	v_exp_f32_e32 v126, v126
	v_exp_f32_e32 v127, v127
	s_waitcnt lgkmcnt(12)
	v_mfma_f32_32x32x16_bf16 v[32:47], v[184:187], v[100:103], v[32:47]
	ds_read_b64_tr_b16 v[184:185], v235 offset:27712
	ds_read_b64_tr_b16 v[186:187], v235 offset:29248
	v_add_f32_e32 v179, v179, v120
	v_add_f32_e32 v202, v202, v121
	v_add_f32_e32 v179, v179, v122
	v_add_f32_e32 v202, v202, v123
	v_add_f32_e32 v179, v179, v124
	v_add_f32_e32 v202, v202, v125
	s_waitcnt lgkmcnt(12)
	v_mfma_f32_32x32x16_bf16 v[16:31], v[188:191], v[100:103], v[16:31]
	ds_read_b64_tr_b16 v[188:189], v235 offset:39936
	ds_read_b64_tr_b16 v[190:191], v235 offset:41472
	v_add_f32_e32 v179, v179, v126
	v_add_f32_e32 v202, v202, v127
	v_cvt_pk_bf16_f32 v108, v120, v121
	v_cvt_pk_bf16_f32 v109, v122, v123
	v_cvt_pk_bf16_f32 v110, v124, v125
	v_cvt_pk_bf16_f32 v111, v126, v127
	s_waitcnt lgkmcnt(12)
	v_mfma_f32_32x32x16_bf16 v[64:79], v[222:225], v[104:107], v[64:79]
	ds_read_b64_tr_b16 v[222:223], v235 offset:40000
	ds_read_b64_tr_b16 v[224:225], v235 offset:41536
	v_max3_f32 v243, v206, v207, v208
	v_max3_f32 v239, v0, v1, v2
	v_max3_f32 v243, v243, v209, v210
	v_max3_f32 v239, v239, v3, v4
	v_max3_f32 v243, v243, v211, v212
	s_waitcnt lgkmcnt(12)
	v_mfma_f32_32x32x16_bf16 v[48:63], v[226:229], v[104:107], v[48:63]
	v_max3_f32 v239, v239, v5, v6
	v_max3_f32 v243, v243, v213, v214
	v_max3_f32 v239, v239, v7, v8
	v_max3_f32 v243, v243, v215, v216
	v_max3_f32 v239, v239, v9, v10
	v_max3_f32 v243, v243, v217, v218
	s_waitcnt lgkmcnt(10)
	v_mfma_f32_32x32x16_bf16 v[32:47], v[230:233], v[104:107], v[32:47]
	v_max3_f32 v239, v239, v11, v12
	v_max3_f32 v243, v243, v219, v220
	v_max3_f32 v239, v239, v13, v14
	v_max_f32_e32 v243, v243, v221
	v_max_f32_e32 v239, v239, v15
	v_max_f32_e32 v243, v243, v239
	s_waitcnt lgkmcnt(8)
	v_mfma_f32_32x32x16_bf16 v[16:31], v[244:247], v[104:107], v[16:31]
	s_waitcnt vmcnt(0)
	v_add3_u32 v238, s38, v178, v160
	v_add3_u32 v239, s38, v180, v160
	ds_write_b128 v238, v[156:159]
	ds_write_b128 v238, v[152:155] offset:9216
	s_waitcnt lgkmcnt(8)
	v_mfma_f32_32x32x16_bf16 v[64:79], v[248:251], v[108:111], v[64:79]
	ds_write_b128 v239, v[148:151] offset:18432
	ds_write_b128 v239, v[144:147] offset:30720
	v_mov_b32_e32 v239, v243
	s_min_i32 s0, s31, 0xf80
	v_add_u32_e32 v238, s0, v181
	v_min_i32_e32 v238, 0x100f, v238
	s_waitcnt lgkmcnt(8)
	v_mfma_f32_32x32x16_bf16 v[48:63], v[184:187], v[108:111], v[48:63]
	v_permlane32_swap_b32_e32 v243, v239
	v_mad_i64_i32 v[192:193], s[0:1], v238, s51, v[162:163]
	global_load_dwordx4 v[156:159], v[192:193], off offset:1024
	global_load_dwordx4 v[152:155], v[192:193], off offset:1152
	s_waitcnt lgkmcnt(6)
	v_mfma_f32_32x32x16_bf16 v[32:47], v[188:191], v[108:111], v[32:47]
	global_load_dwordx4 v[148:151], v[192:193], off offset:2048
	global_load_dwordx4 v[144:147], v[192:193], off offset:2176
	v_max_f32_e32 v243, v243, v239
	s_waitcnt lgkmcnt(4)
	v_mfma_f32_32x32x16_bf16 v[16:31], v[222:225], v[108:111], v[16:31]
	s_mov_b32 s39, s30
	s_mov_b32 s26, s29
	s_mov_b32 s29, s38
	s_add_i32 s0, s38, 0xa800
	s_cmp_lg_u32 s0, 0x1f800
	s_cselect_b32 s38, s0, 0
	s_mov_b32 s35, s31
	v_cmp_lt_f32_e32 vcc, s10, v243
	s_cbranch_vccz .Latt1_o_noresc
; __device__ __forceinline__ void attn_unit_A(const AttnP& P, int u, LAS char* lds) {
;     ...
;         if (more) {
;             if (clsn == 1) A_NEAR(sa0, sa1, t + 1);
;             float mx_; A_ROWMAX(sa0, sa1, mx_);
;             if (__any(mx_ > 8.0f)) { const float dl = fmaxf(mx_, 0.f); const float f_ = __builtin_amdgcn_exp2f(-dl); lrun *= f_;
; #pragma unroll
;                 for (int r = 0; r < 16; ++r) { sa0[r] -= dl; sa1[r] -= dl; negc[r] -= dl; }
; #pragma unroll
;                 for (int d = 0; d < 4; ++d)
; #pragma unroll
;                     for (int r = 0; r < 16; ++r) o[d][r] *= f_; }
;         }
;         bcur = bnext; bnext = bnext + ABUF; if (bnext == 3 * ABUF) bnext = 0;
;     }
;     ...
;     const float inv = 1.0f / (lrun + __shfl_xor(lrun, 32));
	s_nop 11
	v_max_f32_e32 v243, 0, v243
	v_exp_f32_e64 v192, -v243
	v_sub_f32_e32 v80, v80, v243
	v_sub_f32_e32 v81, v81, v243
	v_sub_f32_e32 v82, v82, v243
	v_sub_f32_e32 v83, v83, v243
	v_sub_f32_e32 v84, v84, v243
	v_sub_f32_e32 v85, v85, v243
	v_sub_f32_e32 v86, v86, v243
	v_sub_f32_e32 v87, v87, v243
	v_sub_f32_e32 v88, v88, v243
	v_sub_f32_e32 v89, v89, v243
	v_sub_f32_e32 v90, v90, v243
	v_sub_f32_e32 v91, v91, v243
	v_sub_f32_e32 v92, v92, v243
	v_sub_f32_e32 v93, v93, v243
	v_sub_f32_e32 v94, v94, v243
	v_sub_f32_e32 v95, v95, v243
	v_sub_f32_e32 v206, v206, v243
	v_sub_f32_e32 v207, v207, v243
	v_sub_f32_e32 v208, v208, v243
	v_sub_f32_e32 v209, v209, v243
	v_sub_f32_e32 v210, v210, v243
	v_sub_f32_e32 v211, v211, v243
	v_sub_f32_e32 v212, v212, v243
	v_sub_f32_e32 v213, v213, v243
	v_sub_f32_e32 v214, v214, v243
	v_sub_f32_e32 v215, v215, v243
	v_sub_f32_e32 v216, v216, v243
	v_sub_f32_e32 v217, v217, v243
	v_sub_f32_e32 v218, v218, v243
	v_sub_f32_e32 v219, v219, v243
	v_sub_f32_e32 v220, v220, v243
	v_sub_f32_e32 v221, v221, v243
	v_sub_f32_e32 v0, v0, v243
	v_sub_f32_e32 v1, v1, v243
	v_sub_f32_e32 v2, v2, v243
	v_sub_f32_e32 v3, v3, v243
	v_sub_f32_e32 v4, v4, v243
	v_sub_f32_e32 v5, v5, v243
	v_sub_f32_e32 v6, v6, v243
	v_sub_f32_e32 v7, v7, v243
	v_sub_f32_e32 v8, v8, v243
	v_sub_f32_e32 v9, v9, v243
	v_sub_f32_e32 v10, v10, v243
	v_sub_f32_e32 v11, v11, v243
	v_sub_f32_e32 v12, v12, v243
	v_sub_f32_e32 v13, v13, v243
	v_sub_f32_e32 v14, v14, v243
	v_sub_f32_e32 v15, v15, v243
	v_pk_mul_f32 v[64:65], v[64:65], v[192:193] op_sel_hi:[1,0]
	v_pk_mul_f32 v[66:67], v[66:67], v[192:193] op_sel_hi:[1,0]
	v_pk_mul_f32 v[68:69], v[68:69], v[192:193] op_sel_hi:[1,0]
	v_pk_mul_f32 v[70:71], v[70:71], v[192:193] op_sel_hi:[1,0]
	v_pk_mul_f32 v[72:73], v[72:73], v[192:193] op_sel_hi:[1,0]
	v_pk_mul_f32 v[74:75], v[74:75], v[192:193] op_sel_hi:[1,0]
	v_pk_mul_f32 v[76:77], v[76:77], v[192:193] op_sel_hi:[1,0]
	v_pk_mul_f32 v[78:79], v[78:79], v[192:193] op_sel_hi:[1,0]
	v_pk_mul_f32 v[48:49], v[48:49], v[192:193] op_sel_hi:[1,0]
	v_pk_mul_f32 v[50:51], v[50:51], v[192:193] op_sel_hi:[1,0]
	v_pk_mul_f32 v[52:53], v[52:53], v[192:193] op_sel_hi:[1,0]
	v_pk_mul_f32 v[54:55], v[54:55], v[192:193] op_sel_hi:[1,0]
	v_pk_mul_f32 v[56:57], v[56:57], v[192:193] op_sel_hi:[1,0]
	v_pk_mul_f32 v[58:59], v[58:59], v[192:193] op_sel_hi:[1,0]
	v_pk_mul_f32 v[60:61], v[60:61], v[192:193] op_sel_hi:[1,0]
	v_pk_mul_f32 v[62:63], v[62:63], v[192:193] op_sel_hi:[1,0]
	v_pk_mul_f32 v[32:33], v[32:33], v[192:193] op_sel_hi:[1,0]
	v_pk_mul_f32 v[34:35], v[34:35], v[192:193] op_sel_hi:[1,0]
	v_pk_mul_f32 v[36:37], v[36:37], v[192:193] op_sel_hi:[1,0]
	v_pk_mul_f32 v[38:39], v[38:39], v[192:193] op_sel_hi:[1,0]
	v_pk_mul_f32 v[40:41], v[40:41], v[192:193] op_sel_hi:[1,0]
	v_pk_mul_f32 v[42:43], v[42:43], v[192:193] op_sel_hi:[1,0]
	v_pk_mul_f32 v[44:45], v[44:45], v[192:193] op_sel_hi:[1,0]
	v_pk_mul_f32 v[46:47], v[46:47], v[192:193] op_sel_hi:[1,0]
	v_pk_mul_f32 v[16:17], v[16:17], v[192:193] op_sel_hi:[1,0]
	v_pk_mul_f32 v[18:19], v[18:19], v[192:193] op_sel_hi:[1,0]
	v_pk_mul_f32 v[20:21], v[20:21], v[192:193] op_sel_hi:[1,0]
	v_pk_mul_f32 v[22:23], v[22:23], v[192:193] op_sel_hi:[1,0]
	v_pk_mul_f32 v[24:25], v[24:25], v[192:193] op_sel_hi:[1,0]
	v_pk_mul_f32 v[26:27], v[26:27], v[192:193] op_sel_hi:[1,0]
	v_pk_mul_f32 v[28:29], v[28:29], v[192:193] op_sel_hi:[1,0]
	v_pk_mul_f32 v[30:31], v[30:31], v[192:193] op_sel_hi:[1,0]
	v_mul_f32_e32 v179, v179, v192
	v_mul_f32_e32 v202, v202, v192
	s_nop 1
.Latt1_o_noresc:
	s_waitcnt lgkmcnt(0)
	s_barrier
	s_branch .Latt1_loop
.Latt1_exit:
	v_add_f32_e32 v179, v179, v202
	v_mov_b32_e32 v1, 0
	v_xor_b32_e32 v166, 1, v237
	v_lshlrev_b32_e32 v166, 2, v166
	v_xor_b32_e32 v168, 4, v237
	v_lshlrev_b32_e32 v168, 2, v168
	v_xor_b32_e32 v169, 8, v237
	v_lshlrev_b32_e32 v169, 2, v169
	s_mov_b32 s15, s26
	s_mov_b32 s38, s29
	s_mov_b32 s30, s39
	s_nop 3

; __device__ __forceinline__ unsigned cvtpk(float lo, float hi) { f32x2_t v = {lo, hi}; bf16x2_t b = __builtin_convertvector(v, bf16x2_t); return __builtin_bit_cast(unsigned, b); }
; __device__ __forceinline__ void attn_unit_A(const AttnP& P, int u, LAS char* lds) {
;     ...
;         const float rn = rsqrtf(q * (1.0f / 128.0f) + EPS) * (1.0f - lam_init_of(ly));
;         { bf16_t* op = P.ya + (size_t)(b * LT + tq) * 512 + h * 128; const bool qok = tq < LT;
; #pragma unroll
;             for (int d = 0; d < 4; ++d)
; #pragma unroll
;                 for (int rp = 0; rp < 2; ++rp) { u32x2 w2[2];
; #pragma unroll
;                     for (int k = 0; k < 2; ++k) { const int r4 = 2 * rp + k, dd = d * 32 + 8 * r4 + 4 * hi; const f32x4 gg = *(const f32x4*)(P.subg + dd);
;                         w2[k].x = cvtpk(o[d][4 * r4] * rn * gg[0], o[d][4 * r4 + 1] * rn * gg[1]); w2[k].y = cvtpk(o[d][4 * r4 + 2] * rn * gg[2], o[d][4 * r4 + 3] * rn * gg[3]); }
;                     const u32x4 v = pair16(w2[0], w2[1]);
;                     if (qok) *(u32x4*)(op + d * 32 + 8 * (2 * rp + (hi ? 0 : 1))) = v; }
.LBB0_702:
	s_waitcnt lgkmcnt(0)
	v_add_f32_e32 v0, v0, v20
	v_fmamk_f32 v0, v0, 0x3c000000, v236
	v_cmp_gt_f32_e32 vcc, s50, v0
	v_mul_f32_e32 v20, 0x4b800000, v0
	v_cmp_gt_u32_e64 s[44:45], 32, v171
	v_cndmask_b32_e32 v0, v0, v20, vcc
	v_rsq_f32_e32 v0, v0
	v_cndmask_b32_e64 v23, 0, 8, s[44:45]
	v_readlane_b32 s0, v254, 1
	v_readlane_b32 s1, v254, 2
	v_mul_f32_e32 v20, 0x45800000, v0
	v_cndmask_b32_e32 v0, v0, v20, vcc
	v_sub_f32_e32 v20, 1.0, v21
	v_mul_f32_e32 v22, v0, v20
	v_lshlrev_b32_e32 v0, 2, v161
	global_load_dwordx4 v[96:99], v0, s[46:47]
	global_load_dwordx4 v[100:103], v0, s[46:47] offset:32
	global_load_dwordx4 v[104:107], v0, s[46:47] offset:64
	global_load_dwordx4 v[108:111], v0, s[46:47] offset:96
	global_load_dwordx4 v[112:115], v0, s[46:47] offset:128
	global_load_dwordx4 v[116:119], v0, s[46:47] offset:160
	global_load_dwordx4 v[120:123], v0, s[46:47] offset:192
	global_load_dwordx4 v[124:127], v0, s[46:47] offset:224
	global_load_dwordx4 v[128:131], v0, s[46:47] offset:256
	global_load_dwordx4 v[132:135], v0, s[46:47] offset:288
	global_load_dwordx4 v[136:139], v0, s[46:47] offset:320
	global_load_dwordx4 v[140:143], v0, s[46:47] offset:352
	global_load_dwordx4 v[144:147], v0, s[46:47] offset:384
	global_load_dwordx4 v[148:151], v0, s[46:47] offset:416
	global_load_dwordx4 v[152:155], v0, s[46:47] offset:448
	global_load_dwordx4 v[156:159], v0, s[46:47] offset:480
	s_waitcnt vmcnt(0)
	s_nop 0
	v_pk_mul_f32 v[4:5], v[4:5], v[22:23] op_sel_hi:[1,0]
	v_add_u32_e32 v20, s13, v172
	v_pk_mul_f32 v[2:3], v[2:3], v[22:23] op_sel_hi:[1,0]
	v_ashrrev_i32_e32 v21, 31, v20
	v_lshlrev_b64 v[20:21], 10, v[20:21]
	v_lshl_add_u64 v[20:21], s[0:1], 0, v[20:21]
	v_lshl_add_u64 v[20:21], v[20:21], 0, s[80:81]
	v_cmp_gt_i32_e32 vcc, s37, v172
	s_nop 0
	v_pk_mul_f32 v[4:5], v[96:97], v[4:5]
	v_pk_mul_f32 v[24:25], v[86:87], v[22:23] op_sel_hi:[1,0]
	v_cvt_pk_bf16_f32 v4, v4, v5
	v_pk_mul_f32 v[24:25], v[98:99], v[24:25]
	s_nop 0
	v_cvt_pk_bf16_f32 v5, v24, v25
	s_nop 0
	s_nop 0
	v_pk_mul_f32 v[2:3], v[100:101], v[2:3]
	v_pk_mul_f32 v[24:25], v[84:85], v[22:23] op_sel_hi:[1,0]
	v_cvt_pk_bf16_f32 v2, v2, v3
	v_pk_mul_f32 v[24:25], v[102:103], v[24:25]
	s_nop 0
	v_permlane32_swap_b32_e32 v2, v4
	v_cvt_pk_bf16_f32 v3, v24, v25
	s_nop 1
	v_permlane32_swap_b32_e32 v3, v5
	v_lshlrev_b32_e32 v24, 1, v23
	s_and_saveexec_b64 s[0:1], vcc
	s_cbranch_execz .LBB0_704
	v_mov_b32_e32 v25, v1
	v_lshl_add_u64 v[26:27], v[20:21], 0, v[24:25]
	global_store_dwordx4 v[26:27], v[2:5], off
.LBB0_704:
	s_or_b64 exec, exec, s[0:1]
	v_lshl_add_u64 v[26:27], s[46:47], 0, v[0:1]
	s_nop 0
	v_mov_b32_e32 v23, v22
	v_pk_mul_f32 v[2:3], v[80:81], v[22:23]
	s_nop 0
	v_pk_mul_f32 v[2:3], v[2:3], v[104:105]
	s_nop 0
	v_cvt_pk_bf16_f32 v4, v2, v3
	v_pk_mul_f32 v[2:3], v[82:83], v[22:23]
	s_nop 0
	v_pk_mul_f32 v[2:3], v[2:3], v[106:107]
	s_nop 0
	v_cvt_pk_bf16_f32 v5, v2, v3
	v_pk_mul_f32 v[2:3], v[76:77], v[22:23]
	s_nop 0
	v_pk_mul_f32 v[2:3], v[2:3], v[108:109]
	v_pk_mul_f32 v[28:29], v[78:79], v[22:23]
	v_cvt_pk_bf16_f32 v2, v2, v3
	v_pk_mul_f32 v[28:29], v[28:29], v[110:111]
	s_nop 0
	v_permlane32_swap_b32_e32 v2, v4
	v_cvt_pk_bf16_f32 v3, v28, v29
	s_nop 1
	v_permlane32_swap_b32_e32 v3, v5
	s_and_saveexec_b64 s[0:1], vcc
	s_cbranch_execz .LBB0_706
	v_mov_b32_e32 v25, v1
	v_lshl_add_u64 v[28:29], v[20:21], 0, v[24:25]
	global_store_dwordx4 v[28:29], v[2:5], off offset:32
.LBB0_706:
	s_or_b64 exec, exec, s[0:1]
	s_nop 0
	v_pk_mul_f32 v[2:3], v[72:73], v[22:23]
	s_nop 0
	v_pk_mul_f32 v[2:3], v[2:3], v[112:113]
	s_nop 0
	v_cvt_pk_bf16_f32 v4, v2, v3
	v_pk_mul_f32 v[2:3], v[74:75], v[22:23]
	s_nop 0
	v_pk_mul_f32 v[2:3], v[2:3], v[114:115]
	s_nop 0
	v_cvt_pk_bf16_f32 v5, v2, v3
	v_pk_mul_f32 v[2:3], v[68:69], v[22:23]
	s_nop 0
	v_pk_mul_f32 v[2:3], v[2:3], v[116:117]
	v_pk_mul_f32 v[28:29], v[70:71], v[22:23]
	v_cvt_pk_bf16_f32 v2, v2, v3
	v_pk_mul_f32 v[28:29], v[28:29], v[118:119]
	s_nop 0
	v_permlane32_swap_b32_e32 v2, v4
	v_cvt_pk_bf16_f32 v3, v28, v29
	s_nop 1
	v_permlane32_swap_b32_e32 v3, v5
	s_and_saveexec_b64 s[0:1], vcc
	s_cbranch_execz .LBB0_708
	v_mov_b32_e32 v25, v1
	v_lshl_add_u64 v[28:29], v[20:21], 0, v[24:25]
	global_store_dwordx4 v[28:29], v[2:5], off offset:64
; __device__ __forceinline__ unsigned cvtpk(float lo, float hi) { f32x2_t v = {lo, hi}; bf16x2_t b = __builtin_convertvector(v, bf16x2_t); return __builtin_bit_cast(unsigned, b); }
; __device__ __forceinline__ void attn_unit_A(const AttnP& P, int u, LAS char* lds) {
;     ...
; #pragma unroll
;             for (int d = 0; d < 4; ++d)
; #pragma unroll
;                 for (int rp = 0; rp < 2; ++rp) { u32x2 w2[2];
; #pragma unroll
;                     for (int k = 0; k < 2; ++k) { const int r4 = 2 * rp + k, dd = d * 32 + 8 * r4 + 4 * hi; const f32x4 gg = *(const f32x4*)(P.subg + dd);
;                         w2[k].x = cvtpk(o[d][4 * r4] * rn * gg[0], o[d][4 * r4 + 1] * rn * gg[1]); w2[k].y = cvtpk(o[d][4 * r4 + 2] * rn * gg[2], o[d][4 * r4 + 3] * rn * gg[3]); }
;                     const u32x4 v = pair16(w2[0], w2[1]);
;                     if (qok) *(u32x4*)(op + d * 32 + 8 * (2 * rp + (hi ? 0 : 1))) = v; }
.LBB0_708:
	s_or_b64 exec, exec, s[0:1]
	s_nop 0
	v_pk_mul_f32 v[2:3], v[64:65], v[22:23]
	s_nop 0
	v_pk_mul_f32 v[2:3], v[2:3], v[120:121]
	s_nop 0
	v_cvt_pk_bf16_f32 v4, v2, v3
	v_pk_mul_f32 v[2:3], v[66:67], v[22:23]
	s_nop 0
	v_pk_mul_f32 v[2:3], v[2:3], v[122:123]
	s_nop 0
	v_cvt_pk_bf16_f32 v5, v2, v3
	v_pk_mul_f32 v[2:3], v[56:57], v[22:23]
	s_nop 0
	v_pk_mul_f32 v[2:3], v[2:3], v[124:125]
	v_pk_mul_f32 v[28:29], v[58:59], v[22:23]
	v_cvt_pk_bf16_f32 v2, v2, v3
	v_pk_mul_f32 v[28:29], v[28:29], v[126:127]
	s_nop 0
	v_permlane32_swap_b32_e32 v2, v4
	v_cvt_pk_bf16_f32 v3, v28, v29
	s_nop 1
	v_permlane32_swap_b32_e32 v3, v5
	s_and_saveexec_b64 s[0:1], vcc
	s_cbranch_execz .LBB0_710
	v_mov_b32_e32 v25, v1
	v_lshl_add_u64 v[28:29], v[20:21], 0, v[24:25]
	global_store_dwordx4 v[28:29], v[2:5], off offset:96
.LBB0_710:
	s_or_b64 exec, exec, s[0:1]
	s_nop 0
	v_pk_mul_f32 v[2:3], v[52:53], v[22:23]
	s_nop 0
	v_pk_mul_f32 v[2:3], v[2:3], v[128:129]
	s_nop 0
	v_cvt_pk_bf16_f32 v4, v2, v3
	v_pk_mul_f32 v[2:3], v[54:55], v[22:23]
	s_nop 0
	v_pk_mul_f32 v[2:3], v[2:3], v[130:131]
	s_nop 0
	v_cvt_pk_bf16_f32 v5, v2, v3
	v_pk_mul_f32 v[2:3], v[48:49], v[22:23]
	s_nop 0
	v_pk_mul_f32 v[2:3], v[2:3], v[132:133]
	v_pk_mul_f32 v[28:29], v[50:51], v[22:23]
	v_cvt_pk_bf16_f32 v2, v2, v3
	v_pk_mul_f32 v[28:29], v[28:29], v[134:135]
	s_nop 0
	v_permlane32_swap_b32_e32 v2, v4
	v_cvt_pk_bf16_f32 v3, v28, v29
	s_nop 1
	v_permlane32_swap_b32_e32 v3, v5
	s_and_saveexec_b64 s[0:1], vcc
	s_cbranch_execz .LBB0_712
	v_mov_b32_e32 v25, v1
	v_lshl_add_u64 v[28:29], v[20:21], 0, v[24:25]
	global_store_dwordx4 v[28:29], v[2:5], off offset:128
.LBB0_712:
	s_or_b64 exec, exec, s[0:1]
	s_nop 0
	v_pk_mul_f32 v[2:3], v[38:39], v[22:23]
	s_nop 0
	v_pk_mul_f32 v[2:3], v[2:3], v[136:137]
	s_nop 0
	v_cvt_pk_bf16_f32 v4, v2, v3
	v_pk_mul_f32 v[2:3], v[40:41], v[22:23]
	s_nop 0
	v_pk_mul_f32 v[2:3], v[2:3], v[138:139]
	s_nop 0
	v_cvt_pk_bf16_f32 v5, v2, v3
	v_pk_mul_f32 v[2:3], v[34:35], v[22:23]
	s_nop 0
	v_pk_mul_f32 v[2:3], v[2:3], v[140:141]
	v_pk_mul_f32 v[28:29], v[36:37], v[22:23]
	v_cvt_pk_bf16_f32 v2, v2, v3
	v_pk_mul_f32 v[28:29], v[28:29], v[142:143]
	s_nop 0
	v_permlane32_swap_b32_e32 v2, v4
	v_cvt_pk_bf16_f32 v3, v28, v29
	s_nop 1
	v_permlane32_swap_b32_e32 v3, v5
	s_and_saveexec_b64 s[0:1], vcc
	s_cbranch_execz .LBB0_714
	v_mov_b32_e32 v25, v1
	v_lshl_add_u64 v[28:29], v[20:21], 0, v[24:25]
	global_store_dwordx4 v[28:29], v[2:5], off offset:160
.LBB0_714:
	s_or_b64 exec, exec, s[0:1]
	s_nop 0
	v_pk_mul_f32 v[2:3], v[32:33], v[22:23]
	s_nop 0
	v_pk_mul_f32 v[2:3], v[2:3], v[144:145]
	s_nop 0
	v_cvt_pk_bf16_f32 v4, v2, v3
	v_pk_mul_f32 v[2:3], v[18:19], v[22:23]
	s_nop 0
	v_pk_mul_f32 v[2:3], v[2:3], v[146:147]
	s_nop 0
	v_cvt_pk_bf16_f32 v5, v2, v3
	v_pk_mul_f32 v[2:3], v[14:15], v[22:23]
	v_pk_mul_f32 v[14:15], v[16:17], v[22:23]
	s_nop 0
	v_pk_mul_f32 v[2:3], v[2:3], v[148:149]
	v_pk_mul_f32 v[14:15], v[14:15], v[150:151]
	v_cvt_pk_bf16_f32 v2, v2, v3
	v_cvt_pk_bf16_f32 v3, v14, v15
	s_nop 0
	v_permlane32_swap_b32_e32 v2, v4
	v_permlane32_swap_b32_e32 v3, v5
	s_and_saveexec_b64 s[0:1], vcc
	s_cbranch_execz .LBB0_716
	v_mov_b32_e32 v25, v1
	v_lshl_add_u64 v[14:15], v[20:21], 0, v[24:25]
	global_store_dwordx4 v[14:15], v[2:5], off offset:192
.LBB0_716:
	s_or_b64 exec, exec, s[0:1]
	s_nop 0
	v_pk_mul_f32 v[2:3], v[10:11], v[22:23]
	v_pk_mul_f32 v[6:7], v[6:7], v[22:23]
	s_nop 0
	v_pk_mul_f32 v[2:3], v[2:3], v[152:153]
	s_nop 0
	v_cvt_pk_bf16_f32 v4, v2, v3
	v_pk_mul_f32 v[2:3], v[12:13], v[22:23]
	s_nop 0
	v_pk_mul_f32 v[2:3], v[2:3], v[154:155]
	s_nop 0
	v_pk_mul_f32 v[6:7], v[6:7], v[158:159]
	v_cvt_pk_bf16_f32 v5, v2, v3
	v_pk_mul_f32 v[2:3], v[8:9], v[22:23]
	s_nop 0
	v_pk_mul_f32 v[2:3], v[2:3], v[156:157]
	s_nop 0
	v_cvt_pk_bf16_f32 v2, v2, v3
	v_cvt_pk_bf16_f32 v3, v6, v7
	s_nop 0
	v_permlane32_swap_b32_e32 v2, v4
	v_permlane32_swap_b32_e32 v3, v5
	s_and_saveexec_b64 s[0:1], vcc
	s_cbranch_execz .LBB0_625
	v_mov_b32_e32 v25, v1
	v_lshl_add_u64 v[6:7], v[20:21], 0, v[24:25]
	global_store_dwordx4 v[6:7], v[2:5], off offset:224
	s_branch .LBB0_625

; __device__ __forceinline__ unsigned cvtpk(float lo, float hi) { f32x2_t v = {lo, hi}; bf16x2_t b = __builtin_convertvector(v, bf16x2_t); return __builtin_bit_cast(unsigned, b); }
; __device__ __forceinline__ void attn_unit_A(const AttnP& P, int u, LAS char* lds) {
;     ...
;         const float rn = rsqrtf(q * (1.0f / 128.0f) + EPS) * (1.0f - lam_init_of(ly));
;         { bf16_t* op = P.ya + (size_t)(b * LT + tq) * 512 + h * 128; const bool qok = tq < LT;
; #pragma unroll
;             for (int d = 0; d < 4; ++d)
; #pragma unroll
;                 for (int rp = 0; rp < 2; ++rp) { u32x2 w2[2];
; #pragma unroll
;                     for (int k = 0; k < 2; ++k) { const int r4 = 2 * rp + k, dd = d * 32 + 8 * r4 + 4 * hi; const f32x4 gg = *(const f32x4*)(P.subg + dd);
;                         w2[k].x = cvtpk(o[d][4 * r4] * rn * gg[0], o[d][4 * r4 + 1] * rn * gg[1]); w2[k].y = cvtpk(o[d][4 * r4 + 2] * rn * gg[2], o[d][4 * r4 + 3] * rn * gg[3]); }
;                     const u32x4 v = pair16(w2[0], w2[1]);
;                     if (qok) *(u32x4*)(op + d * 32 + 8 * (2 * rp + (hi ? 0 : 1))) = v; }
.LBB0_795:
	s_waitcnt lgkmcnt(0)
	v_add_f32_e32 v0, v0, v20
	v_fmamk_f32 v0, v0, 0x3c000000, v236
	v_cmp_gt_f32_e32 vcc, s50, v0
	v_mul_f32_e32 v20, 0x4b800000, v0
	v_cmp_gt_u32_e64 s[44:45], 32, v171
	v_cndmask_b32_e32 v0, v0, v20, vcc
	v_rsq_f32_e32 v0, v0
	v_cndmask_b32_e64 v23, 0, 8, s[44:45]
	v_readlane_b32 s0, v255, 12
	v_mul_f32_e32 v20, 0x45800000, v0
	v_cndmask_b32_e32 v0, v0, v20, vcc
	v_sub_f32_e32 v20, 1.0, v21
	v_mul_f32_e32 v22, v0, v20
	v_lshlrev_b32_e32 v0, 2, v161
	global_load_dwordx4 v[96:99], v0, s[46:47]
	global_load_dwordx4 v[100:103], v0, s[46:47] offset:32
	global_load_dwordx4 v[104:107], v0, s[46:47] offset:64
	global_load_dwordx4 v[108:111], v0, s[46:47] offset:96
	global_load_dwordx4 v[112:115], v0, s[46:47] offset:128
	global_load_dwordx4 v[116:119], v0, s[46:47] offset:160
	global_load_dwordx4 v[120:123], v0, s[46:47] offset:192
	global_load_dwordx4 v[124:127], v0, s[46:47] offset:224
	global_load_dwordx4 v[128:131], v0, s[46:47] offset:256
	global_load_dwordx4 v[132:135], v0, s[46:47] offset:288
	global_load_dwordx4 v[136:139], v0, s[46:47] offset:320
	global_load_dwordx4 v[140:143], v0, s[46:47] offset:352
	global_load_dwordx4 v[144:147], v0, s[46:47] offset:384
	global_load_dwordx4 v[148:151], v0, s[46:47] offset:416
	global_load_dwordx4 v[152:155], v0, s[46:47] offset:448
	global_load_dwordx4 v[156:159], v0, s[46:47] offset:480
	s_waitcnt vmcnt(0)
	s_nop 0
	v_pk_mul_f32 v[4:5], v[4:5], v[22:23] op_sel_hi:[1,0]
	v_pk_mul_f32 v[2:3], v[2:3], v[22:23] op_sel_hi:[1,0]
	v_add_u32_e32 v20, s0, v166
	v_ashrrev_i32_e32 v21, 31, v20
	v_readlane_b32 s0, v254, 3
	v_lshlrev_b64 v[20:21], 10, v[20:21]
	v_readlane_b32 s1, v254, 4
	v_cmp_gt_i32_e32 vcc, s37, v166
	s_nop 0
	v_pk_mul_f32 v[4:5], v[96:97], v[4:5]
	v_pk_mul_f32 v[24:25], v[86:87], v[22:23] op_sel_hi:[1,0]
	v_cvt_pk_bf16_f32 v4, v4, v5
	v_pk_mul_f32 v[24:25], v[98:99], v[24:25]
	v_lshl_add_u64 v[20:21], s[0:1], 0, v[20:21]
	v_cvt_pk_bf16_f32 v5, v24, v25
	s_nop 0
	s_nop 0
	v_pk_mul_f32 v[2:3], v[100:101], v[2:3]
	v_pk_mul_f32 v[24:25], v[84:85], v[22:23] op_sel_hi:[1,0]
	v_cvt_pk_bf16_f32 v2, v2, v3
	v_pk_mul_f32 v[24:25], v[102:103], v[24:25]
	s_nop 0
	v_permlane32_swap_b32_e32 v2, v4
	v_cvt_pk_bf16_f32 v3, v24, v25
	s_nop 1
	v_permlane32_swap_b32_e32 v3, v5
	v_lshlrev_b32_e32 v24, 1, v23
	s_and_saveexec_b64 s[0:1], vcc
	s_cbranch_execz .LBB0_797
	v_mov_b32_e32 v25, v1
	v_lshl_add_u64 v[26:27], v[20:21], 0, v[24:25]
	global_store_dwordx4 v[26:27], v[2:5], off

; __device__ __forceinline__ unsigned cvtpk(float lo, float hi) { f32x2_t v = {lo, hi}; bf16x2_t b = __builtin_convertvector(v, bf16x2_t); return __builtin_bit_cast(unsigned, b); }
; __device__ __forceinline__ void attn_unit_A(const AttnP& P, int u, LAS char* lds) {
;     ...
; #pragma unroll
;             for (int d = 0; d < 4; ++d)
; #pragma unroll
;                 for (int rp = 0; rp < 2; ++rp) { u32x2 w2[2];
; #pragma unroll
;                     for (int k = 0; k < 2; ++k) { const int r4 = 2 * rp + k, dd = d * 32 + 8 * r4 + 4 * hi; const f32x4 gg = *(const f32x4*)(P.subg + dd);
;                         w2[k].x = cvtpk(o[d][4 * r4] * rn * gg[0], o[d][4 * r4 + 1] * rn * gg[1]); w2[k].y = cvtpk(o[d][4 * r4 + 2] * rn * gg[2], o[d][4 * r4 + 3] * rn * gg[3]); }
;                     const u32x4 v = pair16(w2[0], w2[1]);
;                     if (qok) *(u32x4*)(op + d * 32 + 8 * (2 * rp + (hi ? 0 : 1))) = v; }
.LBB0_809:
	s_or_b64 exec, exec, s[0:1]
	s_nop 0
	v_pk_mul_f32 v[2:3], v[10:11], v[22:23]
	v_pk_mul_f32 v[6:7], v[6:7], v[22:23]
	s_nop 0
	v_pk_mul_f32 v[2:3], v[2:3], v[152:153]
	s_nop 0
	v_cvt_pk_bf16_f32 v4, v2, v3
	v_pk_mul_f32 v[2:3], v[12:13], v[22:23]
	s_nop 0
	v_pk_mul_f32 v[2:3], v[2:3], v[154:155]
	s_nop 0
	v_pk_mul_f32 v[6:7], v[6:7], v[158:159]
	v_cvt_pk_bf16_f32 v5, v2, v3
	v_pk_mul_f32 v[2:3], v[8:9], v[22:23]
	s_nop 0
	v_pk_mul_f32 v[2:3], v[2:3], v[156:157]
	s_nop 0
	v_cvt_pk_bf16_f32 v2, v2, v3
	v_cvt_pk_bf16_f32 v3, v6, v7
	s_nop 0
	v_permlane32_swap_b32_e32 v2, v4
	v_permlane32_swap_b32_e32 v3, v5
	s_and_saveexec_b64 s[0:1], vcc
	s_cbranch_execz .LBB0_811
	v_mov_b32_e32 v25, v1
	v_lshl_add_u64 v[6:7], v[20:21], 0, v[24:25]
	global_store_dwordx4 v[6:7], v[2:5], off offset:224

; #define LAS __attribute__((address_space(3)))
; template <int MODE> __device__ __forceinline__ void attn_unit(const AttnP& P, int u, LAS char* lds, bool fill) {
;     ...
;     for (int t = 0; t < nt; ++t) {
;         __syncthreads();
; #pragma unroll
;         for (int s = 0; s < NS; ++s) *(LAS u32x4*)(lds + s * ASLOT + lrow * APITCH + lch * 16) = pre[s];
;         __syncthreads();
;         if (t + 1 < nt) ISSUE(t + 1);
;         const int tok0 = TILE_TOK0(t);
;         f32x16 p0, p1;
; #pragma unroll
;         for (int r = 0; r < 16; ++r) { p0[r] = 0.f; p1[r] = 0.f; }
; #pragma unroll
;         for (int ds = 0; ds < 4; ++ds) {
;             const bf16x8 k0 = *(const LAS bf16x8*)(kb + ds * 32);
;             const bf16x8 k1 = *(const LAS bf16x8*)(kb + 32 * APITCH + ds * 32);
;             p0 = __builtin_amdgcn_mfma_f32_32x32x16_bf16(k0, qr[ds], p0, 0, 0, 0);
;             p1 = __builtin_amdgcn_mfma_f32_32x32x16_bf16(k1, qr[ds], p1, 0, 0, 0);
;         }
;         if (MODE == 0) {
;             const bool farl = (tok0 + 63 + 128 <= qtok0), farr = (tok0 - (qtok0 + 31) >= 128) && (tok0 + 64 <= LT);
;             if (farl || farr) { const float cb = farl ? mytab[0] : mytab[256];
; #pragma unroll
;                 for (int r = 0; r < 16; ++r) { p0[r] += cb; p1[r] += cb; } }
;             else {
; #pragma unroll
;                 for (int r = 0; r < 16; ++r) { const int tk0 = tok0 + crow(r, hi), tk1 = tk0 + 32;
;                     int i0 = tk0 - tq + 128; i0 = i0 < 0 ? 0 : (i0 > 256 ? 256 : i0); int i1 = tk1 - tq + 128; i1 = i1 < 0 ? 0 : (i1 > 256 ? 256 : i1);
;                     p0[r] = tk0 < LT ? p0[r] + mytab[i0] : NEGV; p1[r] = tk1 < LT ? p1[r] + mytab[i1] : NEGV; } }
;         } else if (MODE == 2) {
;           if (tok0 >= NMETA && tok0 + 64 <= LT) {
;             const LAS float* t2 = mytab2 + (tok0 - tq + 191 + 4 * hi);
; #pragma unroll
;             for (int r = 0; r < 16; ++r) { p0[r] += t2[(r & 3) + 8 * (r >> 2)]; p1[r] += t2[(r & 3) + 8 * (r >> 2) + 32]; }
;           } else
; #pragma unroll
;             for (int r = 0; r < 16; ++r) { const int tk0 = tok0 + crow(r, hi), tk1 = tk0 + 32; const int r0 = tk0 - tq, r1 = tk1 - tq;
;                 int i0 = r0 + 128; i0 = i0 < 0 ? 0 : (i0 > 256 ? 256 : i0); int i1 = r1 + 128; i1 = i1 < 0 ? 0 : (i1 > 256 ? 256 : i1);
.LBB0_1174:
	v_sub_f32_e32 v133, v133, v167
	v_sub_f32_e32 v135, v135, v167
	v_sub_f32_e32 v137, v137, v167
	v_sub_f32_e32 v139, v139, v167
	v_sub_f32_e32 v141, v141, v167
	v_sub_f32_e32 v143, v143, v167
	v_sub_f32_e32 v145, v145, v167
	v_sub_f32_e32 v147, v147, v167
	v_sub_f32_e32 v149, v149, v167
	v_sub_f32_e32 v151, v151, v167
	v_sub_f32_e32 v153, v153, v167
	v_sub_f32_e32 v155, v155, v167
	v_sub_f32_e32 v157, v157, v167
	v_sub_f32_e32 v159, v159, v167
	v_sub_f32_e32 v161, v161, v167
	v_sub_f32_e32 v163, v163, v167
	v_sub_f32_e32 v134, v134, v167
	v_sub_f32_e32 v136, v136, v167
	v_sub_f32_e32 v138, v138, v167
	v_sub_f32_e32 v140, v140, v167
	v_sub_f32_e32 v142, v142, v167
	v_sub_f32_e32 v144, v144, v167
	v_sub_f32_e32 v146, v146, v167
	v_sub_f32_e32 v148, v148, v167
	v_sub_f32_e32 v150, v150, v167
	v_sub_f32_e32 v152, v152, v167
	v_sub_f32_e32 v154, v154, v167
	v_sub_f32_e32 v156, v156, v167
	v_sub_f32_e32 v158, v158, v167
	v_sub_f32_e32 v160, v160, v167
	v_sub_f32_e32 v162, v162, v167
	v_sub_f32_e32 v164, v164, v167
.Lnat1_loop:
	s_waitcnt lgkmcnt(0)
	s_barrier
	s_waitcnt vmcnt(7)
	ds_write_b128 v165, v[82:85]
	s_waitcnt vmcnt(6)
	ds_write_b128 v165, v[86:89] offset:9216
	s_waitcnt vmcnt(5)
	ds_write_b128 v165, v[90:93] offset:18432
	s_waitcnt vmcnt(4)
	ds_write_b128 v165, v[94:97] offset:27648
	s_waitcnt vmcnt(3)
	ds_write_b128 v165, v[98:101] offset:36864
	s_waitcnt vmcnt(2)
	ds_write_b128 v165, v[102:105] offset:46080
	s_waitcnt vmcnt(1)
	ds_write_b128 v165, v[106:109] offset:55296
	s_waitcnt vmcnt(0)
	ds_write_b128 v165, v[110:113] offset:64512
	s_waitcnt lgkmcnt(0)
	s_barrier
	s_cmpk_eq_i32 s12, 0x1c0
	s_cbranch_scc1 .Lnat1_noload
	v_add_u32_e32 v34, s12, v115
	v_min_i32_e32 v34, 0x100f, v34
	v_mad_i64_i32 v[34:35], s[14:15], v34, s51, v[126:127]
	v_lshl_add_u64 v[36:37], v[34:35], 0, s[80:81]
	s_mov_b32 s1, s81
	s_mov_b32 s39, s81
	v_lshl_add_u64 v[38:39], v[34:35], 0, s[0:1]
	global_load_dwordx4 v[82:85], v[36:37], off
	global_load_dwordx4 v[86:89], v[38:39], off
	v_lshl_add_u64 v[36:37], v[34:35], 0, s[38:39]
	s_mov_b32 s43, s81
	s_mov_b32 s47, s81
	v_lshl_add_u64 v[38:39], v[34:35], 0, s[42:43]
	global_load_dwordx4 v[90:93], v[36:37], off
	global_load_dwordx4 v[94:97], v[38:39], off
	v_lshl_add_u64 v[36:37], v[34:35], 0, s[46:47]
	s_mov_b32 s49, s81
	s_mov_b32 s59, s81
	v_lshl_add_u64 v[38:39], v[34:35], 0, s[48:49]
	global_load_dwordx4 v[98:101], v[36:37], off
	global_load_dwordx4 v[102:105], v[38:39], off
	v_lshl_add_u64 v[36:37], v[34:35], 0, s[58:59]
	s_mov_b32 s61, s81
	v_lshl_add_u64 v[34:35], v[34:35], 0, s[60:61]
	global_load_dwordx4 v[106:109], v[36:37], off
	global_load_dwordx4 v[110:113], v[34:35], off
.Lnat1_noload:
	v_mov_b32_e32 v117, s17
	v_cndmask_b32_e64 v117, v117, v116, s[44:45]
	v_lshl_add_u32 v184, v132, 2, v117
	ds_read_b128 v[118:121], v0
	ds_read_b128 v[128:131], v0 offset:4608
	ds_read_b128 v[168:171], v0 offset:32
	ds_read_b128 v[172:175], v0 offset:4640
	ds_read_b128 v[176:179], v0 offset:64
	ds_read_b128 v[180:183], v0 offset:4672
	ds_read2_b32 v[50:51], v184 offset0:0 offset1:1
	ds_read2_b32 v[52:53], v184 offset0:2 offset1:3
	ds_read2_b32 v[54:55], v184 offset0:8 offset1:9
	ds_read2_b32 v[56:57], v184 offset0:10 offset1:11
	ds_read2_b32 v[58:59], v184 offset0:16 offset1:17
	ds_read2_b32 v[60:61], v184 offset0:18 offset1:19
	ds_read2_b32 v[62:63], v184 offset0:24 offset1:25
	ds_read2_b32 v[64:65], v184 offset0:26 offset1:27
	ds_read2_b32 v[34:35], v184 offset0:32 offset1:33
	ds_read2_b32 v[36:37], v184 offset0:34 offset1:35
	ds_read2_b32 v[38:39], v184 offset0:40 offset1:41
	ds_read2_b32 v[40:41], v184 offset0:42 offset1:43
	ds_read2_b32 v[42:43], v184 offset0:48 offset1:49
	ds_read2_b32 v[44:45], v184 offset0:50 offset1:51
	ds_read2_b32 v[46:47], v184 offset0:56 offset1:57
	ds_read2_b32 v[48:49], v184 offset0:58 offset1:59
	s_waitcnt lgkmcnt(15)
	v_add_f32_e32 v50, v50, v133
	v_add_f32_e32 v51, v51, v135
	s_waitcnt lgkmcnt(14)
	v_add_f32_e32 v52, v52, v137
	v_add_f32_e32 v53, v53, v139
	s_waitcnt lgkmcnt(13)
	v_add_f32_e32 v54, v54, v141
	v_add_f32_e32 v55, v55, v143
	s_waitcnt lgkmcnt(12)
	v_add_f32_e32 v56, v56, v145
	v_add_f32_e32 v57, v57, v147
	s_waitcnt lgkmcnt(11)
	v_add_f32_e32 v58, v58, v149
	v_add_f32_e32 v59, v59, v151
	s_waitcnt lgkmcnt(10)
	v_add_f32_e32 v60, v60, v153
	v_add_f32_e32 v61, v61, v155
	s_waitcnt lgkmcnt(9)
	v_add_f32_e32 v62, v62, v157
	v_add_f32_e32 v63, v63, v159
	s_waitcnt lgkmcnt(8)
	v_add_f32_e32 v64, v64, v161
	v_add_f32_e32 v65, v65, v163
	s_waitcnt lgkmcnt(7)
	v_add_f32_e32 v34, v34, v134
	v_add_f32_e32 v35, v35, v136
	s_waitcnt lgkmcnt(6)
	v_add_f32_e32 v36, v36, v138
	v_add_f32_e32 v37, v37, v140
	s_waitcnt lgkmcnt(5)
	v_add_f32_e32 v38, v38, v142
	v_add_f32_e32 v39, v39, v144
	s_waitcnt lgkmcnt(4)
	v_add_f32_e32 v40, v40, v146
	v_add_f32_e32 v41, v41, v148
	s_waitcnt lgkmcnt(3)
	v_add_f32_e32 v42, v42, v150
	v_add_f32_e32 v43, v43, v152
	s_waitcnt lgkmcnt(2)
	v_add_f32_e32 v44, v44, v154
	v_add_f32_e32 v45, v45, v156
	s_waitcnt lgkmcnt(1)
	v_add_f32_e32 v46, v46, v158
	v_add_f32_e32 v47, v47, v160
	s_waitcnt lgkmcnt(0)
	v_add_f32_e32 v48, v48, v162
	v_add_f32_e32 v49, v49, v164
	v_mfma_f32_32x32x16_bf16 v[50:65], v[118:121], v[66:69], v[50:65]
	ds_read_b128 v[118:121], v0 offset:96
	v_mfma_f32_32x32x16_bf16 v[34:49], v[128:131], v[66:69], v[34:49]
	ds_read_b128 v[128:131], v0 offset:4704
	v_mfma_f32_32x32x16_bf16 v[50:65], v[168:171], v[70:73], v[50:65]
	ds_read_b64_tr_b16 v[168:169], v166 offset:9216
	ds_read_b64_tr_b16 v[170:171], v166 offset:10368
	v_mfma_f32_32x32x16_bf16 v[34:49], v[172:175], v[70:73], v[34:49]
	ds_read_b64_tr_b16 v[172:173], v166 offset:9280
	ds_read_b64_tr_b16 v[174:175], v166 offset:10432
	v_mfma_f32_32x32x16_bf16 v[50:65], v[176:179], v[74:77], v[50:65]
	ds_read_b64_tr_b16 v[176:177], v166 offset:11520
	ds_read_b64_tr_b16 v[178:179], v166 offset:12672
	v_mfma_f32_32x32x16_bf16 v[34:49], v[180:183], v[74:77], v[34:49]
	ds_read_b64_tr_b16 v[180:181], v166 offset:11584
	ds_read_b64_tr_b16 v[182:183], v166 offset:12736
	s_waitcnt lgkmcnt(9)
; template <int MODE> __device__ __forceinline__ void attn_unit(const AttnP& P, int u, LAS char* lds, bool fill) {
;     ...
;         float mx = p0[0];
; #pragma unroll
;         for (int r = 1; r < 16; ++r) mx = fmaxf(mx, p0[r]);
; #pragma unroll
;         for (int r = 0; r < 16; ++r) mx = fmaxf(mx, p1[r]);
;         { const auto rr = __builtin_amdgcn_permlane32_swap(__float_as_uint(mx), __float_as_uint(mx), false, false); mx = fmaxf(__uint_as_float(rr[0]), __uint_as_float(rr[1])); }
;         if (__any(mx > mrun + 8.0f)) {
;             const float mnew = fmaxf(mrun, mx); const float f = __builtin_amdgcn_exp2f(mrun - mnew); mrun = mnew; lrun *= f;
; #pragma unroll
;             for (int d = 0; d < ND; ++d)
; #pragma unroll
;                 for (int r = 0; r < 16; ++r) o[d][r] *= f;
;         }
	v_mfma_f32_32x32x16_bf16 v[50:65], v[118:121], v[78:81], v[50:65]
	s_waitcnt lgkmcnt(8)
	v_mfma_f32_32x32x16_bf16 v[34:49], v[128:131], v[78:81], v[34:49]
	ds_read_b64_tr_b16 v[118:119], v166 offset:13824
	ds_read_b64_tr_b16 v[120:121], v166 offset:14976
	ds_read_b64_tr_b16 v[128:129], v166 offset:13888
	ds_read_b64_tr_b16 v[130:131], v166 offset:15040
	s_nop 7
	v_max3_f32 v117, v50, v51, v52
	v_max3_f32 v184, v34, v35, v36
	v_max3_f32 v117, v117, v53, v54
	v_max3_f32 v184, v184, v37, v38
	v_max3_f32 v117, v117, v55, v56
	v_max3_f32 v184, v184, v39, v40
	v_max3_f32 v117, v117, v57, v58
	v_max3_f32 v184, v184, v41, v42
	v_max3_f32 v117, v117, v59, v60
	v_max3_f32 v184, v184, v43, v44
	v_max3_f32 v117, v117, v61, v62
	v_max3_f32 v184, v184, v45, v46
	v_max3_f32 v117, v117, v63, v64
	v_max3_f32 v184, v184, v47, v48
	v_max_f32_e32 v117, v117, v65
	v_max_f32_e32 v184, v184, v49
	v_max_f32_e32 v117, v117, v184
	v_mov_b32_e32 v184, v117
	s_nop 1
	v_permlane32_swap_b32_e32 v117, v184
	v_max_f32_e32 v117, v117, v184
	v_cmp_lt_f32_e32 vcc, 0x41000000, v117
	s_cbranch_vccz .Lnat1_noresc
	v_max_f32_e32 v117, 0, v117
	v_exp_f32_e64 v184, -v117
	v_add_f32_e32 v167, v167, v117
	v_sub_f32_e32 v133, v133, v117
	v_sub_f32_e32 v135, v135, v117
	v_sub_f32_e32 v137, v137, v117
	v_sub_f32_e32 v139, v139, v117
	v_sub_f32_e32 v141, v141, v117
	v_sub_f32_e32 v143, v143, v117
	v_sub_f32_e32 v145, v145, v117
	v_sub_f32_e32 v147, v147, v117
	v_sub_f32_e32 v149, v149, v117
	v_sub_f32_e32 v151, v151, v117
	v_sub_f32_e32 v153, v153, v117
	v_sub_f32_e32 v155, v155, v117
	v_sub_f32_e32 v157, v157, v117
	v_sub_f32_e32 v159, v159, v117
	v_sub_f32_e32 v161, v161, v117
	v_sub_f32_e32 v163, v163, v117
	v_sub_f32_e32 v134, v134, v117
	v_sub_f32_e32 v136, v136, v117
	v_sub_f32_e32 v138, v138, v117
	v_sub_f32_e32 v140, v140, v117
	v_sub_f32_e32 v142, v142, v117
	v_sub_f32_e32 v144, v144, v117
	v_sub_f32_e32 v146, v146, v117
	v_sub_f32_e32 v148, v148, v117
	v_sub_f32_e32 v150, v150, v117
	v_sub_f32_e32 v152, v152, v117
	v_sub_f32_e32 v154, v154, v117
	v_sub_f32_e32 v156, v156, v117
	v_sub_f32_e32 v158, v158, v117
	v_sub_f32_e32 v160, v160, v117
	v_sub_f32_e32 v162, v162, v117
	v_sub_f32_e32 v164, v164, v117
	v_sub_f32_e32 v50, v50, v117
	v_sub_f32_e32 v51, v51, v117
	v_sub_f32_e32 v52, v52, v117
	v_sub_f32_e32 v53, v53, v117
	v_sub_f32_e32 v54, v54, v117
	v_sub_f32_e32 v55, v55, v117
	v_sub_f32_e32 v56, v56, v117
	v_sub_f32_e32 v57, v57, v117
	v_sub_f32_e32 v58, v58, v117
	v_sub_f32_e32 v59, v59, v117
	v_sub_f32_e32 v60, v60, v117
	v_sub_f32_e32 v61, v61, v117
	v_sub_f32_e32 v62, v62, v117
	v_sub_f32_e32 v63, v63, v117
	v_sub_f32_e32 v64, v64, v117
	v_sub_f32_e32 v65, v65, v117
	v_sub_f32_e32 v34, v34, v117
	v_sub_f32_e32 v35, v35, v117
	v_sub_f32_e32 v36, v36, v117
	v_sub_f32_e32 v37, v37, v117
	v_sub_f32_e32 v38, v38, v117
	v_sub_f32_e32 v39, v39, v117
	v_sub_f32_e32 v40, v40, v117
	v_sub_f32_e32 v41, v41, v117
	v_sub_f32_e32 v42, v42, v117
	v_sub_f32_e32 v43, v43, v117
	v_sub_f32_e32 v44, v44, v117
	v_sub_f32_e32 v45, v45, v117
	v_sub_f32_e32 v46, v46, v117
	v_sub_f32_e32 v47, v47, v117
	v_sub_f32_e32 v48, v48, v117
	v_sub_f32_e32 v49, v49, v117
	v_mul_f32_e32 v2, v2, v184
	v_mul_f32_e32 v3, v3, v184
	v_mul_f32_e32 v4, v4, v184
	v_mul_f32_e32 v5, v5, v184
	v_mul_f32_e32 v6, v6, v184
	v_mul_f32_e32 v7, v7, v184
	v_mul_f32_e32 v8, v8, v184
	v_mul_f32_e32 v9, v9, v184
	v_mul_f32_e32 v10, v10, v184
	v_mul_f32_e32 v11, v11, v184
	v_mul_f32_e32 v12, v12, v184
	v_mul_f32_e32 v13, v13, v184
	v_mul_f32_e32 v14, v14, v184
	v_mul_f32_e32 v15, v15, v184
	v_mul_f32_e32 v16, v16, v184
	v_mul_f32_e32 v17, v17, v184
	v_mul_f32_e32 v18, v18, v184
	v_mul_f32_e32 v19, v19, v184
	v_mul_f32_e32 v20, v20, v184
	v_mul_f32_e32 v21, v21, v184
	v_mul_f32_e32 v22, v22, v184
	v_mul_f32_e32 v23, v23, v184
	v_mul_f32_e32 v24, v24, v184
	v_mul_f32_e32 v25, v25, v184
	v_mul_f32_e32 v26, v26, v184
	v_mul_f32_e32 v27, v27, v184
	v_mul_f32_e32 v28, v28, v184
	v_mul_f32_e32 v29, v29, v184
	v_mul_f32_e32 v30, v30, v184
	v_mul_f32_e32 v31, v31, v184
	v_mul_f32_e32 v32, v32, v184
	v_mul_f32_e32 v33, v33, v184
	v_mul_f32_e32 v114, v114, v184
	s_nop 1
; #define LAS __attribute__((address_space(3)))
; __device__ __forceinline__ unsigned cvtpk(float lo, float hi) { f32x2_t v = {lo, hi}; bf16x2_t b = __builtin_convertvector(v, bf16x2_t); return __builtin_bit_cast(unsigned, b); }
; __device__ __forceinline__ s16x4 vtr(const LAS char* p) { return __builtin_bit_cast(s16x4, __builtin_amdgcn_ds_read_tr16_b64_v4i16((LAS s16x4*)p)); }
; template <int MODE> __device__ __forceinline__ void attn_unit(const AttnP& P, int u, LAS char* lds, bool fill) {
;     ...
;         float sacc = 0.f;
; #pragma unroll
;         for (int r = 0; r < 16; ++r) { p0[r] = __builtin_amdgcn_exp2f(p0[r] - mrun); p1[r] = __builtin_amdgcn_exp2f(p1[r] - mrun); sacc += p0[r] + p1[r]; }
;         lrun += sacc;
;         bf16x8 pf[4];
;         { u32x4 a;
;           a.x = cvtpk(p0[0], p0[1]); a.y = cvtpk(p0[2], p0[3]); a.z = cvtpk(p0[4], p0[5]); a.w = cvtpk(p0[6], p0[7]); pf[0] = __builtin_bit_cast(bf16x8, a);
;           a.x = cvtpk(p0[8], p0[9]); a.y = cvtpk(p0[10], p0[11]); a.z = cvtpk(p0[12], p0[13]); a.w = cvtpk(p0[14], p0[15]); pf[1] = __builtin_bit_cast(bf16x8, a);
;           a.x = cvtpk(p1[0], p1[1]); a.y = cvtpk(p1[2], p1[3]); a.z = cvtpk(p1[4], p1[5]); a.w = cvtpk(p1[6], p1[7]); pf[2] = __builtin_bit_cast(bf16x8, a);
;           a.x = cvtpk(p1[8], p1[9]); a.y = cvtpk(p1[10], p1[11]); a.z = cvtpk(p1[12], p1[13]); a.w = cvtpk(p1[14], p1[15]); pf[3] = __builtin_bit_cast(bf16x8, a); }
; #pragma unroll
;         for (int d = 0; d < ND; ++d) {
;             const int vslot = MODE == 0 ? 2 + (d >> 1) : MODE == 1 ? kslot + 1 : 1;
;             const LAS char* vb = lds + vslot * ASLOT + vrow * APITCH + (d & 1) * 64 + vcolb;
; #pragma unroll
;             for (int ks = 0; ks < 4; ++ks) {
;                 const s16x4 vl = vtr(vb + (16 * ks) * APITCH), vh = vtr(vb + (16 * ks + 8) * APITCH);
;                 const bf16x8 vf = (bf16x8){vl[0], vl[1], vl[2], vl[3], vh[0], vh[1], vh[2], vh[3]};
;                 o[d] = __builtin_amdgcn_mfma_f32_32x32x16_bf16(vf, pf[ks], o[d], 0, 0, 0);
;             }
;         }
.Lnat1_noresc:
	v_exp_f32_e32 v50, v50
	v_exp_f32_e32 v51, v51
	v_exp_f32_e32 v52, v52
	v_exp_f32_e32 v53, v53
	v_exp_f32_e32 v54, v54
	v_exp_f32_e32 v55, v55
	v_exp_f32_e32 v56, v56
	v_exp_f32_e32 v57, v57
	v_add_f32_e32 v114, v114, v50
	v_add_f32_e32 v114, v114, v51
	v_add_f32_e32 v114, v114, v52
	v_add_f32_e32 v114, v114, v53
	v_add_f32_e32 v114, v114, v54
	v_add_f32_e32 v114, v114, v55
	v_add_f32_e32 v114, v114, v56
	v_add_f32_e32 v114, v114, v57
	v_cvt_pk_bf16_f32 v50, v50, v51
	v_cvt_pk_bf16_f32 v51, v52, v53
	v_cvt_pk_bf16_f32 v52, v54, v55
	v_cvt_pk_bf16_f32 v53, v56, v57
	s_nop 0
	s_waitcnt lgkmcnt(10)
	v_mfma_f32_32x32x16_bf16 v[2:17], v[168:171], v[50:53], v[2:17]
	ds_read_b64_tr_b16 v[168:169], v166 offset:16128
	ds_read_b64_tr_b16 v[170:171], v166 offset:17280
	v_exp_f32_e32 v58, v58
	v_exp_f32_e32 v59, v59
	v_exp_f32_e32 v60, v60
	v_exp_f32_e32 v61, v61
	v_exp_f32_e32 v62, v62
	v_exp_f32_e32 v63, v63
	v_exp_f32_e32 v64, v64
	v_exp_f32_e32 v65, v65
	v_add_f32_e32 v114, v114, v58
	v_add_f32_e32 v114, v114, v59
	v_add_f32_e32 v114, v114, v60
	v_add_f32_e32 v114, v114, v61
	v_add_f32_e32 v114, v114, v62
	v_add_f32_e32 v114, v114, v63
	v_add_f32_e32 v114, v114, v64
	v_add_f32_e32 v114, v114, v65
	v_cvt_pk_bf16_f32 v54, v58, v59
	v_cvt_pk_bf16_f32 v55, v60, v61
	v_cvt_pk_bf16_f32 v56, v62, v63
	v_cvt_pk_bf16_f32 v57, v64, v65
	s_waitcnt lgkmcnt(10)
	v_mfma_f32_32x32x16_bf16 v[18:33], v[172:175], v[50:53], v[18:33]
	ds_read_b64_tr_b16 v[172:173], v166 offset:16192
	ds_read_b64_tr_b16 v[174:175], v166 offset:17344
	s_waitcnt lgkmcnt(10)
	v_mfma_f32_32x32x16_bf16 v[2:17], v[176:179], v[54:57], v[2:17]
	v_exp_f32_e32 v34, v34
	v_exp_f32_e32 v35, v35
	v_exp_f32_e32 v36, v36
	v_exp_f32_e32 v37, v37
	v_exp_f32_e32 v38, v38
	v_exp_f32_e32 v39, v39
	v_exp_f32_e32 v40, v40
	v_exp_f32_e32 v41, v41
	v_add_f32_e32 v114, v114, v34
	v_add_f32_e32 v114, v114, v35
	v_add_f32_e32 v114, v114, v36
	v_add_f32_e32 v114, v114, v37
	v_add_f32_e32 v114, v114, v38
	v_add_f32_e32 v114, v114, v39
	v_add_f32_e32 v114, v114, v40
	v_add_f32_e32 v114, v114, v41
	v_cvt_pk_bf16_f32 v58, v34, v35
	v_cvt_pk_bf16_f32 v59, v36, v37
	v_cvt_pk_bf16_f32 v60, v38, v39
	v_cvt_pk_bf16_f32 v61, v40, v41
	s_waitcnt lgkmcnt(8)
	v_mfma_f32_32x32x16_bf16 v[18:33], v[180:183], v[54:57], v[18:33]
	s_waitcnt lgkmcnt(6)
	v_mfma_f32_32x32x16_bf16 v[2:17], v[118:121], v[58:61], v[2:17]
	v_exp_f32_e32 v42, v42
	v_exp_f32_e32 v43, v43
	v_exp_f32_e32 v44, v44
	v_exp_f32_e32 v45, v45
	v_exp_f32_e32 v46, v46
	v_exp_f32_e32 v47, v47
	v_exp_f32_e32 v48, v48
	v_exp_f32_e32 v49, v49
	v_add_f32_e32 v114, v114, v42
	v_add_f32_e32 v114, v114, v43
	v_add_f32_e32 v114, v114, v44
	v_add_f32_e32 v114, v114, v45
	v_add_f32_e32 v114, v114, v46
	v_add_f32_e32 v114, v114, v47
	v_add_f32_e32 v114, v114, v48
	v_add_f32_e32 v114, v114, v49
	v_cvt_pk_bf16_f32 v62, v42, v43
	v_cvt_pk_bf16_f32 v63, v44, v45
	v_cvt_pk_bf16_f32 v64, v46, v47
	v_cvt_pk_bf16_f32 v65, v48, v49
	s_waitcnt lgkmcnt(4)
	v_mfma_f32_32x32x16_bf16 v[18:33], v[128:131], v[58:61], v[18:33]
	s_nop 0
	s_waitcnt lgkmcnt(2)
	v_mfma_f32_32x32x16_bf16 v[2:17], v[168:171], v[62:65], v[2:17]
	s_waitcnt lgkmcnt(0)
	v_mfma_f32_32x32x16_bf16 v[18:33], v[172:175], v[62:65], v[18:33]
	s_add_i32 s12, s12, 64
	v_add_u32_e32 v116, 0x7c, v116
	s_cmpk_eq_i32 s12, 0x200
	s_cbranch_scc0 .Lnat1_loop
	s_branch .LBB0_1178

; #define LAS __attribute__((address_space(3)))
; #define ISSUE(t) do { int tok_ = TILE_TOK0(t) + lrow; tok_ = tok_ > LT - 1 ? LT - 1 : tok_; const bf16_t* src_ = pb + (size_t)tok_ * INC; \
;         _Pragma("unroll") for (int s = 0; s < NS; ++s) pre[s] = *(const u32x4*)(src_ + STREAM_COL(s)); } while (0)
; template <int MODE> __device__ __forceinline__ void attn_unit(const AttnP& P, int u, LAS char* lds, bool fill) {
;     ...
;     for (int t = 0; t < nt; ++t) {
;         __syncthreads();
; #pragma unroll
;         for (int s = 0; s < NS; ++s) *(LAS u32x4*)(lds + s * ASLOT + lrow * APITCH + lch * 16) = pre[s];
;         __syncthreads();
;         if (t + 1 < nt) ISSUE(t + 1);
;         const int tok0 = TILE_TOK0(t);
;         f32x16 p0, p1;
; #pragma unroll
;         for (int r = 0; r < 16; ++r) { p0[r] = 0.f; p1[r] = 0.f; }
; #pragma unroll
;         for (int ds = 0; ds < 4; ++ds) {
;             const bf16x8 k0 = *(const LAS bf16x8*)(kb + ds * 32);
;             const bf16x8 k1 = *(const LAS bf16x8*)(kb + 32 * APITCH + ds * 32);
;             p0 = __builtin_amdgcn_mfma_f32_32x32x16_bf16(k0, qr[ds], p0, 0, 0, 0);
;             p1 = __builtin_amdgcn_mfma_f32_32x32x16_bf16(k1, qr[ds], p1, 0, 0, 0);
;         }
.Lnat2_loop:
	s_waitcnt lgkmcnt(0)
	s_barrier
	s_waitcnt vmcnt(7)
	ds_write_b128 v165, v[82:85]
	s_waitcnt vmcnt(6)
	ds_write_b128 v165, v[86:89] offset:9216
	s_waitcnt vmcnt(5)
	ds_write_b128 v165, v[90:93] offset:18432
	s_waitcnt vmcnt(4)
	ds_write_b128 v165, v[94:97] offset:27648
	s_waitcnt vmcnt(3)
	ds_write_b128 v165, v[98:101] offset:36864
	s_waitcnt vmcnt(2)
	ds_write_b128 v165, v[102:105] offset:46080
	s_waitcnt vmcnt(1)
	ds_write_b128 v165, v[106:109] offset:55296
	s_waitcnt vmcnt(0)
	ds_write_b128 v165, v[110:113] offset:64512
	s_waitcnt lgkmcnt(0)
	s_barrier
	s_cmpk_eq_i32 s13, 0x1c0
	s_cbranch_scc1 .Lnat2_noload
	v_add_u32_e32 v34, s13, v115
	v_min_i32_e32 v34, 0x100f, v34
	v_mad_i64_i32 v[34:35], s[14:15], v34, s51, v[126:127]
	v_lshl_add_u64 v[36:37], s[42:43], 1, v[34:35]
	v_lshl_add_u64 v[38:39], s[58:59], 1, v[34:35]
	global_load_dwordx4 v[82:85], v[36:37], off
	global_load_dwordx4 v[86:89], v[38:39], off
	v_lshl_add_u64 v[36:37], s[60:61], 1, v[34:35]
	v_lshl_add_u64 v[38:39], s[62:63], 1, v[34:35]
	global_load_dwordx4 v[90:93], v[36:37], off
	global_load_dwordx4 v[94:97], v[38:39], off
	v_lshl_add_u64 v[36:37], s[64:65], 1, v[34:35]
	v_lshl_add_u64 v[38:39], s[66:67], 1, v[34:35]
	global_load_dwordx4 v[98:101], v[36:37], off
	global_load_dwordx4 v[102:105], v[38:39], off
	v_lshl_add_u64 v[36:37], s[38:39], 1, v[34:35]
	v_lshl_add_u64 v[34:35], s[0:1], 1, v[34:35]
	global_load_dwordx4 v[106:109], v[36:37], off
	global_load_dwordx4 v[110:113], v[34:35], off

; #define LAS __attribute__((address_space(3)))
; __device__ __forceinline__ unsigned cvtpk(float lo, float hi) { f32x2_t v = {lo, hi}; bf16x2_t b = __builtin_convertvector(v, bf16x2_t); return __builtin_bit_cast(unsigned, b); }
; __device__ __forceinline__ s16x4 vtr(const LAS char* p) { return __builtin_bit_cast(s16x4, __builtin_amdgcn_ds_read_tr16_b64_v4i16((LAS s16x4*)p)); }
; template <int MODE> __device__ __forceinline__ void attn_unit(const AttnP& P, int u, LAS char* lds, bool fill) {
;     ...
;         float sacc = 0.f;
; #pragma unroll
;         for (int r = 0; r < 16; ++r) { p0[r] = __builtin_amdgcn_exp2f(p0[r] - mrun); p1[r] = __builtin_amdgcn_exp2f(p1[r] - mrun); sacc += p0[r] + p1[r]; }
;         lrun += sacc;
;         bf16x8 pf[4];
;         { u32x4 a;
;           a.x = cvtpk(p0[0], p0[1]); a.y = cvtpk(p0[2], p0[3]); a.z = cvtpk(p0[4], p0[5]); a.w = cvtpk(p0[6], p0[7]); pf[0] = __builtin_bit_cast(bf16x8, a);
;           a.x = cvtpk(p0[8], p0[9]); a.y = cvtpk(p0[10], p0[11]); a.z = cvtpk(p0[12], p0[13]); a.w = cvtpk(p0[14], p0[15]); pf[1] = __builtin_bit_cast(bf16x8, a);
;           a.x = cvtpk(p1[0], p1[1]); a.y = cvtpk(p1[2], p1[3]); a.z = cvtpk(p1[4], p1[5]); a.w = cvtpk(p1[6], p1[7]); pf[2] = __builtin_bit_cast(bf16x8, a);
;           a.x = cvtpk(p1[8], p1[9]); a.y = cvtpk(p1[10], p1[11]); a.z = cvtpk(p1[12], p1[13]); a.w = cvtpk(p1[14], p1[15]); pf[3] = __builtin_bit_cast(bf16x8, a); }
; #pragma unroll
;         for (int d = 0; d < ND; ++d) {
;             const int vslot = MODE == 0 ? 2 + (d >> 1) : MODE == 1 ? kslot + 1 : 1;
;             const LAS char* vb = lds + vslot * ASLOT + vrow * APITCH + (d & 1) * 64 + vcolb;
; #pragma unroll
;             for (int ks = 0; ks < 4; ++ks) {
;                 const s16x4 vl = vtr(vb + (16 * ks) * APITCH), vh = vtr(vb + (16 * ks + 8) * APITCH);
;                 const bf16x8 vf = (bf16x8){vl[0], vl[1], vl[2], vl[3], vh[0], vh[1], vh[2], vh[3]};
;                 o[d] = __builtin_amdgcn_mfma_f32_32x32x16_bf16(vf, pf[ks], o[d], 0, 0, 0);
;             }
;         }
.Lnat2_noresc:
	v_exp_f32_e32 v50, v50
	v_exp_f32_e32 v51, v51
	v_exp_f32_e32 v52, v52
	v_exp_f32_e32 v53, v53
	v_exp_f32_e32 v54, v54
	v_exp_f32_e32 v55, v55
	v_exp_f32_e32 v56, v56
	v_exp_f32_e32 v57, v57
	v_add_f32_e32 v114, v114, v50
	v_add_f32_e32 v114, v114, v51
	v_add_f32_e32 v114, v114, v52
	v_add_f32_e32 v114, v114, v53
	v_add_f32_e32 v114, v114, v54
	v_add_f32_e32 v114, v114, v55
	v_add_f32_e32 v114, v114, v56
	v_add_f32_e32 v114, v114, v57
	v_cvt_pk_bf16_f32 v50, v50, v51
	v_cvt_pk_bf16_f32 v51, v52, v53
	v_cvt_pk_bf16_f32 v52, v54, v55
	v_cvt_pk_bf16_f32 v53, v56, v57
	s_nop 0
	s_waitcnt lgkmcnt(10)
	v_mfma_f32_32x32x16_bf16 v[2:17], v[168:171], v[50:53], v[2:17]
	ds_read_b64_tr_b16 v[168:169], v166 offset:16128
	ds_read_b64_tr_b16 v[170:171], v166 offset:17280
	v_exp_f32_e32 v58, v58
	v_exp_f32_e32 v59, v59
	v_exp_f32_e32 v60, v60
	v_exp_f32_e32 v61, v61
	v_exp_f32_e32 v62, v62
	v_exp_f32_e32 v63, v63
	v_exp_f32_e32 v64, v64
	v_exp_f32_e32 v65, v65
	v_add_f32_e32 v114, v114, v58
	v_add_f32_e32 v114, v114, v59
	v_add_f32_e32 v114, v114, v60
	v_add_f32_e32 v114, v114, v61
	v_add_f32_e32 v114, v114, v62
	v_add_f32_e32 v114, v114, v63
	v_add_f32_e32 v114, v114, v64
	v_add_f32_e32 v114, v114, v65
	v_cvt_pk_bf16_f32 v54, v58, v59
	v_cvt_pk_bf16_f32 v55, v60, v61
	v_cvt_pk_bf16_f32 v56, v62, v63
	v_cvt_pk_bf16_f32 v57, v64, v65
	s_waitcnt lgkmcnt(10)
	v_mfma_f32_32x32x16_bf16 v[18:33], v[172:175], v[50:53], v[18:33]
	ds_read_b64_tr_b16 v[172:173], v166 offset:16192
	ds_read_b64_tr_b16 v[174:175], v166 offset:17344
	s_waitcnt lgkmcnt(10)
	v_mfma_f32_32x32x16_bf16 v[2:17], v[176:179], v[54:57], v[2:17]
	v_exp_f32_e32 v34, v34
	v_exp_f32_e32 v35, v35
	v_exp_f32_e32 v36, v36
	v_exp_f32_e32 v37, v37
	v_exp_f32_e32 v38, v38
	v_exp_f32_e32 v39, v39
	v_exp_f32_e32 v40, v40
	v_exp_f32_e32 v41, v41
	v_add_f32_e32 v114, v114, v34
	v_add_f32_e32 v114, v114, v35
	v_add_f32_e32 v114, v114, v36
	v_add_f32_e32 v114, v114, v37
	v_add_f32_e32 v114, v114, v38
	v_add_f32_e32 v114, v114, v39
	v_add_f32_e32 v114, v114, v40
	v_add_f32_e32 v114, v114, v41
	v_cvt_pk_bf16_f32 v58, v34, v35
	v_cvt_pk_bf16_f32 v59, v36, v37
	v_cvt_pk_bf16_f32 v60, v38, v39
	v_cvt_pk_bf16_f32 v61, v40, v41
	s_waitcnt lgkmcnt(8)
	v_mfma_f32_32x32x16_bf16 v[18:33], v[180:183], v[54:57], v[18:33]
	s_waitcnt lgkmcnt(6)
	v_mfma_f32_32x32x16_bf16 v[2:17], v[118:121], v[58:61], v[2:17]
	v_exp_f32_e32 v42, v42
	v_exp_f32_e32 v43, v43
	v_exp_f32_e32 v44, v44
	v_exp_f32_e32 v45, v45
	v_exp_f32_e32 v46, v46
	v_exp_f32_e32 v47, v47
	v_exp_f32_e32 v48, v48
	v_exp_f32_e32 v49, v49
	v_add_f32_e32 v114, v114, v42
	v_add_f32_e32 v114, v114, v43
	v_add_f32_e32 v114, v114, v44
	v_add_f32_e32 v114, v114, v45
	v_add_f32_e32 v114, v114, v46
	v_add_f32_e32 v114, v114, v47
	v_add_f32_e32 v114, v114, v48
	v_add_f32_e32 v114, v114, v49
	v_cvt_pk_bf16_f32 v62, v42, v43
	v_cvt_pk_bf16_f32 v63, v44, v45
	v_cvt_pk_bf16_f32 v64, v46, v47
	v_cvt_pk_bf16_f32 v65, v48, v49
	s_waitcnt lgkmcnt(4)
	v_mfma_f32_32x32x16_bf16 v[18:33], v[128:131], v[58:61], v[18:33]
	s_nop 0
	s_waitcnt lgkmcnt(2)
	v_mfma_f32_32x32x16_bf16 v[2:17], v[168:171], v[62:65], v[2:17]
	s_waitcnt lgkmcnt(0)
	v_mfma_f32_32x32x16_bf16 v[18:33], v[172:175], v[62:65], v[18:33]
	s_add_i32 s13, s13, 64
	v_add_u32_e32 v116, 0x7c, v116
	s_cmpk_eq_i32 s13, 0x200
	s_cbranch_scc0 .Lnat2_loop
	s_branch .LBB0_1365
